# baseline (speedup 1.0000x reference)
; #define PG8_STAGE(bufoff, gbase, voff) do { _Pragma("unroll") for (int _i = 0; _i < 2; ++_i) \
;         __builtin_amdgcn_global_load_lds((const unsigned*)((const char*)(gbase) + (voff)[_i]), (LAS unsigned*)(lds + (bufoff) + ldsw + _i * 8192), 16, 0, 0); } while (0)
; #define PG8_LDA(dst, b, h) do { _Pragma("unroll") for (int m = 0; m < 4; ++m) _Pragma("unroll") for (int k = 0; k < 2; ++k) dst[m][k] = *(const LAS bf16x8*)(lds + PG8_SA(b, h) + aoff + m * 2048 + k * 1024); } while (0)
; #define PG8_LDB(dst, b, h) do { _Pragma("unroll") for (int n = 0; n < 2; ++n) _Pragma("unroll") for (int k = 0; k < 2; ++k) dst[n][k] = *(const LAS bf16x8*)(lds + PG8_SB(b, h) + boff + n * 2048 + k * 1024); } while (0)
; #define PG8_MMA(ai, bj, At, Bt) do { __builtin_amdgcn_s_setprio(1); _Pragma("unroll") for (int m = 0; m < 4; ++m) _Pragma("unroll") for (int n = 0; n < 2; ++n) _Pragma("unroll") for (int k = 0; k < 2; ++k) \
;         acc[ai][bj][m][n] = __builtin_amdgcn_mfma_f32_16x16x32_bf16(Bt[n][k], At[m][k], acc[ai][bj][m][n], 0, 0, 0); __builtin_amdgcn_s_setprio(0); } while (0)
; #define PG8_WAIT_V(n) asm volatile("s_waitcnt vmcnt(" #n ")" ::: "memory")
; #define PG8_WAIT_L(n) asm volatile("s_waitcnt lgkmcnt(" #n ")" ::: "memory")
; #define PG8_BAR __builtin_amdgcn_s_barrier()
; #define PG8_SCHED __builtin_amdgcn_sched_barrier(0)
;     ...
;             PG8_LDB(B0, 0, 0); PG8_SCHED; PG8_LDA(At, 0, 0); PG8_STAGE(PG8_SA(1, 1), a1 + hstep, voffA);
;             PG8_WAIT_L(8); PG8_BAR; PG8_WAIT_L(0); PG8_MMA(0, 0, At, B0); PG8_BAR; PG8_SCHED;
;             PG8_LDB(B1, 0, 1); PG8_STAGE(PG8_SB(0, 0), b2, voffB);
;             PG8_BAR; PG8_WAIT_L(0); PG8_MMA(0, 1, At, B1); PG8_BAR;
;             PG8_LDA(At, 0, 1); PG8_STAGE(PG8_SA(0, 0), a2, voffA);
;             PG8_BAR; PG8_WAIT_L(0); PG8_MMA(1, 0, At, B0); PG8_BAR; PG8_SCHED;
;             PG8_STAGE(PG8_SB(0, 1), b2 + hstep, voffB);
;             PG8_WAIT_V(6); PG8_BAR; PG8_MMA(1, 1, At, B1); PG8_BAR;
;             PG8_LDB(B0, 1, 0); PG8_SCHED; PG8_LDA(At, 1, 0); PG8_STAGE(PG8_SA(0, 1), a2 + hstep, voffA);
;             PG8_WAIT_L(8); PG8_BAR; PG8_WAIT_L(0); PG8_MMA(0, 0, At, B0); PG8_BAR; PG8_SCHED;
.LBB0_120:
	s_add_i32 s44, s2, 2
	s_add_u32 s10, s8, 0x100
	s_addc_u32 s11, s9, 0
	s_add_i32 s35, 0, 0x10000
	v_add_u32_e32 v156, s35, v145
	ds_read_b128 v[140:143], v156
	ds_read_b128 v[148:151], v156 offset:1024
	ds_read_b128 v[152:155], v156 offset:2048
	ds_read_b128 v[156:159], v156 offset:3072
	s_cmp_eq_u32 s41, s2
	s_cselect_b32 s2, s6, s10
	s_cselect_b32 s3, s7, s11
	s_cselect_b32 s13, s19, s43
	s_cselect_b32 s12, s18, s42
	v_lshl_add_u64 v[192:193], s[8:9], 0, v[136:137]
	s_add_i32 m0, s21, 0xc000
	ds_read_b128 v[160:163], v147
	ds_read_b128 v[164:167], v147 offset:1024
	ds_read_b128 v[168:171], v147 offset:2048
	ds_read_b128 v[172:175], v147 offset:3072
	ds_read_b128 v[176:179], v147 offset:4096
	ds_read_b128 v[180:183], v147 offset:5120
	ds_read_b128 v[184:187], v147 offset:6144
	ds_read_b128 v[188:191], v147 offset:7168
	global_load_lds_dwordx4 v[192:193], off
	v_lshl_add_u64 v[192:193], s[8:9], 0, v[138:139]
	s_add_i32 m0, s21, 0xe000
	s_nop 0
	global_load_lds_dwordx4 v[192:193], off
	s_waitcnt lgkmcnt(8)
	s_barrier
	s_waitcnt lgkmcnt(0)
	s_setprio 1
	s_waitcnt lgkmcnt(0)
	v_mfma_f32_16x16x32_bf16 v[126:129], v[140:143], v[160:163], v[126:129]
	v_mfma_f32_16x16x32_bf16 v[122:125], v[152:155], v[160:163], v[122:125]
	v_mfma_f32_16x16x32_bf16 v[110:113], v[140:143], v[168:171], v[110:113]
	v_mfma_f32_16x16x32_bf16 v[106:109], v[152:155], v[168:171], v[106:109]
	v_mfma_f32_16x16x32_bf16 v[94:97], v[140:143], v[176:179], v[94:97]
	v_mfma_f32_16x16x32_bf16 v[90:93], v[152:155], v[176:179], v[90:93]
	v_mfma_f32_16x16x32_bf16 v[78:81], v[140:143], v[184:187], v[78:81]
	v_mfma_f32_16x16x32_bf16 v[74:77], v[152:155], v[184:187], v[74:77]
	v_mfma_f32_16x16x32_bf16 v[126:129], v[148:151], v[164:167], v[126:129]
	v_mfma_f32_16x16x32_bf16 v[122:125], v[156:159], v[164:167], v[122:125]
	v_mfma_f32_16x16x32_bf16 v[110:113], v[148:151], v[172:175], v[110:113]
	v_mfma_f32_16x16x32_bf16 v[106:109], v[156:159], v[172:175], v[106:109]
	v_mfma_f32_16x16x32_bf16 v[94:97], v[148:151], v[180:183], v[94:97]
	v_mfma_f32_16x16x32_bf16 v[90:93], v[156:159], v[180:183], v[90:93]
	v_mfma_f32_16x16x32_bf16 v[78:81], v[148:151], v[188:191], v[78:81]
	v_mfma_f32_16x16x32_bf16 v[74:77], v[156:159], v[188:191], v[74:77]
	s_setprio 0
	s_barrier
	s_add_i32 s45, 0, 0x14000
	v_add_u32_e32 v208, s45, v145
	s_add_i32 s8, s35, s20
	ds_read_b128 v[192:195], v208
	ds_read_b128 v[196:199], v208 offset:1024
	ds_read_b128 v[220:223], v208 offset:2048
	ds_read_b128 v[224:227], v208 offset:3072
	v_lshl_add_u64 v[208:209], s[12:13], 0, v[64:65]
	s_mov_b32 m0, s8
	v_lshl_add_u64 v[210:211], s[12:13], 0, v[134:135]
	global_load_lds_dwordx4 v[208:209], off
	s_add_i32 m0, s8, 0x2000
	s_nop 0
	global_load_lds_dwordx4 v[210:211], off
	s_barrier
	s_waitcnt lgkmcnt(0)
	s_setprio 1
	s_waitcnt lgkmcnt(0)
	v_mfma_f32_16x16x32_bf16 v[118:121], v[192:195], v[160:163], v[118:121]
	v_mfma_f32_16x16x32_bf16 v[114:117], v[220:223], v[160:163], v[114:117]
	v_mfma_f32_16x16x32_bf16 v[102:105], v[192:195], v[168:171], v[102:105]
	v_mfma_f32_16x16x32_bf16 v[98:101], v[220:223], v[168:171], v[98:101]
	v_mfma_f32_16x16x32_bf16 v[86:89], v[192:195], v[176:179], v[86:89]
	v_mfma_f32_16x16x32_bf16 v[82:85], v[220:223], v[176:179], v[82:85]
	v_mfma_f32_16x16x32_bf16 v[70:73], v[192:195], v[184:187], v[70:73]
	v_mfma_f32_16x16x32_bf16 v[66:69], v[220:223], v[184:187], v[66:69]
	v_mfma_f32_16x16x32_bf16 v[118:121], v[196:199], v[164:167], v[118:121]
	v_mfma_f32_16x16x32_bf16 v[114:117], v[224:227], v[164:167], v[114:117]
	v_mfma_f32_16x16x32_bf16 v[102:105], v[196:199], v[172:175], v[102:105]
	v_mfma_f32_16x16x32_bf16 v[98:101], v[224:227], v[172:175], v[98:101]
	v_mfma_f32_16x16x32_bf16 v[86:89], v[196:199], v[180:183], v[86:89]
	v_mfma_f32_16x16x32_bf16 v[82:85], v[224:227], v[180:183], v[82:85]
	v_mfma_f32_16x16x32_bf16 v[70:73], v[196:199], v[188:191], v[70:73]
	v_mfma_f32_16x16x32_bf16 v[66:69], v[224:227], v[188:191], v[66:69]
	s_setprio 0
	s_mov_b32 m0, s21
	v_lshl_add_u64 v[212:213], s[2:3], 0, v[130:131]
	s_barrier
	ds_read_b128 v[160:163], v147 offset:16384
	ds_read_b128 v[164:167], v147 offset:17408
	ds_read_b128 v[168:171], v147 offset:18432
	ds_read_b128 v[172:175], v147 offset:19456
	ds_read_b128 v[176:179], v147 offset:20480
	ds_read_b128 v[180:183], v147 offset:21504
	ds_read_b128 v[184:187], v147 offset:22528
	ds_read_b128 v[188:191], v147 offset:23552
	global_load_lds_dwordx4 v[212:213], off
	v_lshl_add_u64 v[214:215], s[2:3], 0, v[132:133]
	s_mov_b32 m0, s22
	s_nop 0
	global_load_lds_dwordx4 v[214:215], off
	s_barrier
	s_waitcnt lgkmcnt(0)
	s_setprio 1
	s_waitcnt lgkmcnt(0)
	v_mfma_f32_16x16x32_bf16 v[60:63], v[140:143], v[160:163], v[60:63]
	v_mfma_f32_16x16x32_bf16 v[56:59], v[152:155], v[160:163], v[56:59]
	v_mfma_f32_16x16x32_bf16 v[44:47], v[140:143], v[168:171], v[44:47]
	v_mfma_f32_16x16x32_bf16 v[40:43], v[152:155], v[168:171], v[40:43]
	v_mfma_f32_16x16x32_bf16 v[28:31], v[140:143], v[176:179], v[28:31]
	v_mfma_f32_16x16x32_bf16 v[24:27], v[152:155], v[176:179], v[24:27]
	v_mfma_f32_16x16x32_bf16 v[12:15], v[140:143], v[184:187], v[12:15]
	v_mfma_f32_16x16x32_bf16 v[8:11], v[152:155], v[184:187], v[8:11]
	v_mfma_f32_16x16x32_bf16 v[60:63], v[148:151], v[164:167], v[60:63]
	v_mfma_f32_16x16x32_bf16 v[56:59], v[156:159], v[164:167], v[56:59]
	v_mfma_f32_16x16x32_bf16 v[44:47], v[148:151], v[172:175], v[44:47]
	v_mfma_f32_16x16x32_bf16 v[40:43], v[156:159], v[172:175], v[40:43]
	v_mfma_f32_16x16x32_bf16 v[28:31], v[148:151], v[180:183], v[28:31]
	v_mfma_f32_16x16x32_bf16 v[24:27], v[156:159], v[180:183], v[24:27]
	v_mfma_f32_16x16x32_bf16 v[12:15], v[148:151], v[188:191], v[12:15]
	v_mfma_f32_16x16x32_bf16 v[8:11], v[156:159], v[188:191], v[8:11]
	s_setprio 0
	s_barrier
; #define PG8_STAGE(bufoff, gbase, voff) do { _Pragma("unroll") for (int _i = 0; _i < 2; ++_i) \
;         __builtin_amdgcn_global_load_lds((const unsigned*)((const char*)(gbase) + (voff)[_i]), (LAS unsigned*)(lds + (bufoff) + ldsw + _i * 8192), 16, 0, 0); } while (0)
; #define PG8_LDA(dst, b, h) do { _Pragma("unroll") for (int m = 0; m < 4; ++m) _Pragma("unroll") for (int k = 0; k < 2; ++k) dst[m][k] = *(const LAS bf16x8*)(lds + PG8_SA(b, h) + aoff + m * 2048 + k * 1024); } while (0)
; #define PG8_LDB(dst, b, h) do { _Pragma("unroll") for (int n = 0; n < 2; ++n) _Pragma("unroll") for (int k = 0; k < 2; ++k) dst[n][k] = *(const LAS bf16x8*)(lds + PG8_SB(b, h) + boff + n * 2048 + k * 1024); } while (0)
; #define PG8_MMA(ai, bj, At, Bt) do { __builtin_amdgcn_s_setprio(1); _Pragma("unroll") for (int m = 0; m < 4; ++m) _Pragma("unroll") for (int n = 0; n < 2; ++n) _Pragma("unroll") for (int k = 0; k < 2; ++k) \
;         acc[ai][bj][m][n] = __builtin_amdgcn_mfma_f32_16x16x32_bf16(Bt[n][k], At[m][k], acc[ai][bj][m][n], 0, 0, 0); __builtin_amdgcn_s_setprio(0); } while (0)
; #define PG8_WAIT_V(n) asm volatile("s_waitcnt vmcnt(" #n ")" ::: "memory")
; #define PG8_WAIT_L(n) asm volatile("s_waitcnt lgkmcnt(" #n ")" ::: "memory")
; #define PG8_BAR __builtin_amdgcn_s_barrier()
; #define PG8_SCHED __builtin_amdgcn_sched_barrier(0)
;     ...
;             PG8_WAIT_V(6); PG8_BAR; PG8_MMA(1, 1, At, B1); PG8_BAR;
;             PG8_LDB(B0, 1, 0); PG8_SCHED; PG8_LDA(At, 1, 0); PG8_STAGE(PG8_SA(0, 1), a2 + hstep, voffA);
;             PG8_WAIT_L(8); PG8_BAR; PG8_WAIT_L(0); PG8_MMA(0, 0, At, B0); PG8_BAR; PG8_SCHED;
;             PG8_LDB(B1, 1, 1); PG8_STAGE(PG8_SB(1, 0), b3, voffB);
;             PG8_BAR; PG8_WAIT_L(0); PG8_MMA(0, 1, At, B1); PG8_BAR;
;             PG8_LDA(At, 1, 1); PG8_STAGE(PG8_SA(1, 0), a3, voffA);
;             PG8_BAR; PG8_WAIT_L(0); PG8_MMA(1, 0, At, B0); PG8_BAR; PG8_SCHED;
;             PG8_STAGE(PG8_SB(1, 1), b3 + hstep, voffB);
;             PG8_WAIT_V(6); PG8_BAR; PG8_MMA(1, 1, At, B1); PG8_BAR;
	s_add_u32 s8, s12, 0x84000
	s_addc_u32 s9, s13, 0
	s_add_i32 s35, s45, s20
	v_lshl_add_u64 v[140:141], s[8:9], 0, v[64:65]
	s_mov_b32 m0, s35
	s_nop 0
	global_load_lds_dwordx4 v[140:141], off
	v_lshl_add_u64 v[140:141], s[8:9], 0, v[134:135]
	s_add_i32 m0, s35, 0x2000
	s_nop 0
	global_load_lds_dwordx4 v[140:141], off
	s_waitcnt vmcnt(6)
	s_barrier
	s_setprio 1
	v_mfma_f32_16x16x32_bf16 v[52:55], v[192:195], v[160:163], v[52:55]
	v_mfma_f32_16x16x32_bf16 v[48:51], v[220:223], v[160:163], v[48:51]
	v_mfma_f32_16x16x32_bf16 v[36:39], v[192:195], v[168:171], v[36:39]
	v_mfma_f32_16x16x32_bf16 v[32:35], v[220:223], v[168:171], v[32:35]
	v_mfma_f32_16x16x32_bf16 v[20:23], v[192:195], v[176:179], v[20:23]
	v_mfma_f32_16x16x32_bf16 v[16:19], v[220:223], v[176:179], v[16:19]
	v_mfma_f32_16x16x32_bf16 v[4:7], v[192:195], v[184:187], v[4:7]
	v_mfma_f32_16x16x32_bf16 v[0:3], v[220:223], v[184:187], v[0:3]
	v_mfma_f32_16x16x32_bf16 v[52:55], v[196:199], v[164:167], v[52:55]
	v_mfma_f32_16x16x32_bf16 v[48:51], v[224:227], v[164:167], v[48:51]
	v_mfma_f32_16x16x32_bf16 v[36:39], v[196:199], v[172:175], v[36:39]
	v_mfma_f32_16x16x32_bf16 v[32:35], v[224:227], v[172:175], v[32:35]
	v_mfma_f32_16x16x32_bf16 v[20:23], v[196:199], v[180:183], v[20:23]
	v_mfma_f32_16x16x32_bf16 v[16:19], v[224:227], v[180:183], v[16:19]
	v_mfma_f32_16x16x32_bf16 v[4:7], v[196:199], v[188:191], v[4:7]
	v_mfma_f32_16x16x32_bf16 v[0:3], v[224:227], v[188:191], v[0:3]
	s_setprio 0
	s_add_i32 s8, 0, 0x18000
	v_add_u32_e32 v156, s8, v145
	s_barrier
	ds_read_b128 v[140:143], v156
	ds_read_b128 v[148:151], v156 offset:1024
	ds_read_b128 v[152:155], v156 offset:2048
	ds_read_b128 v[156:159], v156 offset:3072
	s_add_u32 s2, s2, 0x84000
	s_addc_u32 s3, s3, 0
	s_mov_b32 m0, s23
	v_lshl_add_u64 v[192:193], s[2:3], 0, v[130:131]
	ds_read_b128 v[160:163], v147 offset:32768
	ds_read_b128 v[164:167], v147 offset:33792
	ds_read_b128 v[168:171], v147 offset:34816
	ds_read_b128 v[172:175], v147 offset:35840
	ds_read_b128 v[176:179], v147 offset:36864
	ds_read_b128 v[180:183], v147 offset:37888
	ds_read_b128 v[184:187], v147 offset:38912
	ds_read_b128 v[188:191], v147 offset:39936
	global_load_lds_dwordx4 v[192:193], off
	v_lshl_add_u64 v[192:193], s[2:3], 0, v[132:133]
	s_mov_b32 m0, s24
	s_nop 0
	global_load_lds_dwordx4 v[192:193], off
	s_waitcnt lgkmcnt(8)
	s_barrier
	s_waitcnt lgkmcnt(0)
	s_setprio 1
	s_waitcnt lgkmcnt(0)
	v_mfma_f32_16x16x32_bf16 v[126:129], v[140:143], v[160:163], v[126:129]
	v_mfma_f32_16x16x32_bf16 v[122:125], v[152:155], v[160:163], v[122:125]
	v_mfma_f32_16x16x32_bf16 v[110:113], v[140:143], v[168:171], v[110:113]
	v_mfma_f32_16x16x32_bf16 v[106:109], v[152:155], v[168:171], v[106:109]
	v_mfma_f32_16x16x32_bf16 v[94:97], v[140:143], v[176:179], v[94:97]
	v_mfma_f32_16x16x32_bf16 v[90:93], v[152:155], v[176:179], v[90:93]
	v_mfma_f32_16x16x32_bf16 v[78:81], v[140:143], v[184:187], v[78:81]
	v_mfma_f32_16x16x32_bf16 v[74:77], v[152:155], v[184:187], v[74:77]
	v_mfma_f32_16x16x32_bf16 v[126:129], v[148:151], v[164:167], v[126:129]
	v_mfma_f32_16x16x32_bf16 v[122:125], v[156:159], v[164:167], v[122:125]
	v_mfma_f32_16x16x32_bf16 v[110:113], v[148:151], v[172:175], v[110:113]
	v_mfma_f32_16x16x32_bf16 v[106:109], v[156:159], v[172:175], v[106:109]
	v_mfma_f32_16x16x32_bf16 v[94:97], v[148:151], v[180:183], v[94:97]
	v_mfma_f32_16x16x32_bf16 v[90:93], v[156:159], v[180:183], v[90:93]
	v_mfma_f32_16x16x32_bf16 v[78:81], v[148:151], v[188:191], v[78:81]
	v_mfma_f32_16x16x32_bf16 v[74:77], v[156:159], v[188:191], v[74:77]
	s_setprio 0
	s_barrier
	s_add_i32 s9, 0, 0x1c000
	s_add_i32 s2, s8, s20
	v_add_u32_e32 v219, s9, v145
	v_lshl_add_u64 v[208:209], v[208:209], 0, s[16:17]
	s_mov_b32 m0, s2
	ds_read_b128 v[192:195], v219
	ds_read_b128 v[196:199], v219 offset:1024
	ds_read_b128 v[220:223], v219 offset:2048
	ds_read_b128 v[224:227], v219 offset:3072
	global_load_lds_dwordx4 v[208:209], off
	v_lshl_add_u64 v[208:209], v[210:211], 0, s[16:17]
	s_add_i32 m0, s2, 0x2000
	s_nop 0
	global_load_lds_dwordx4 v[208:209], off
	s_barrier
	s_waitcnt lgkmcnt(0)
	s_setprio 1
	s_waitcnt lgkmcnt(0)
	v_mfma_f32_16x16x32_bf16 v[118:121], v[192:195], v[160:163], v[118:121]
	v_mfma_f32_16x16x32_bf16 v[114:117], v[220:223], v[160:163], v[114:117]
	v_mfma_f32_16x16x32_bf16 v[102:105], v[192:195], v[168:171], v[102:105]
	v_mfma_f32_16x16x32_bf16 v[98:101], v[220:223], v[168:171], v[98:101]
	v_mfma_f32_16x16x32_bf16 v[86:89], v[192:195], v[176:179], v[86:89]
	v_mfma_f32_16x16x32_bf16 v[82:85], v[220:223], v[176:179], v[82:85]
	v_mfma_f32_16x16x32_bf16 v[70:73], v[192:195], v[184:187], v[70:73]
	v_mfma_f32_16x16x32_bf16 v[66:69], v[220:223], v[184:187], v[66:69]
	v_mfma_f32_16x16x32_bf16 v[118:121], v[196:199], v[164:167], v[118:121]
	v_mfma_f32_16x16x32_bf16 v[114:117], v[224:227], v[164:167], v[114:117]
	v_mfma_f32_16x16x32_bf16 v[102:105], v[196:199], v[172:175], v[102:105]
	v_mfma_f32_16x16x32_bf16 v[98:101], v[224:227], v[172:175], v[98:101]
	v_mfma_f32_16x16x32_bf16 v[86:89], v[196:199], v[180:183], v[86:89]
	v_mfma_f32_16x16x32_bf16 v[82:85], v[224:227], v[180:183], v[82:85]
	v_mfma_f32_16x16x32_bf16 v[70:73], v[196:199], v[188:191], v[70:73]
	v_mfma_f32_16x16x32_bf16 v[66:69], v[224:227], v[188:191], v[66:69]
	s_setprio 0
	s_mov_b32 m0, s25
	v_lshl_add_u64 v[208:209], v[212:213], 0, s[16:17]
	s_barrier
	ds_read_b128 v[160:163], v147 offset:49152
	ds_read_b128 v[164:167], v147 offset:50176
	ds_read_b128 v[168:171], v147 offset:51200
	ds_read_b128 v[172:175], v147 offset:52224
	ds_read_b128 v[176:179], v147 offset:53248
	ds_read_b128 v[180:183], v147 offset:54272
	ds_read_b128 v[184:187], v147 offset:55296
	ds_read_b128 v[188:191], v147 offset:56320
	global_load_lds_dwordx4 v[208:209], off
	v_lshl_add_u64 v[208:209], v[214:215], 0, s[16:17]
	s_mov_b32 m0, s26
	s_nop 0
	global_load_lds_dwordx4 v[208:209], off
	s_barrier
; __device__ __forceinline__ unsigned cvt_pk_bf16(float lo, float hi) { unsigned r; asm volatile("v_cvt_pk_bf16_f32 %0, %1, %2" : "=v"(r) : "v"(lo), "v"(hi)); return r; }
; #define PG8_STAGE(bufoff, gbase, voff) do { _Pragma("unroll") for (int _i = 0; _i < 2; ++_i) \
;         __builtin_amdgcn_global_load_lds((const unsigned*)((const char*)(gbase) + (voff)[_i]), (LAS unsigned*)(lds + (bufoff) + ldsw + _i * 8192), 16, 0, 0); } while (0)
; #define PG8_LDA(dst, b, h) do { _Pragma("unroll") for (int m = 0; m < 4; ++m) _Pragma("unroll") for (int k = 0; k < 2; ++k) dst[m][k] = *(const LAS bf16x8*)(lds + PG8_SA(b, h) + aoff + m * 2048 + k * 1024); } while (0)
; #define PG8_WAIT_V(n) asm volatile("s_waitcnt vmcnt(" #n ")" ::: "memory")
;     __device__ __forceinline__ void operator()(const f32x4 (&acc)[2][2][4][2], const Unit& u, int wr, int wc, int fr, int fq) const {
;         const int row0 = u.pm * BM + wr * 64 + fr, col0 = u.pn * BM + wc * 32 + 8 * fq;
; #pragma unroll
;         for (int ai = 0; ai < 2; ++ai)
; #pragma unroll
;             for (int m = 0; m < 4; ++m) { bf16_t* rowp = O + (size_t)(row0 + ai * HALF + m * 16) * LDF + col0;
; #pragma unroll
;                 for (int bj = 0; bj < 2; ++bj) { f32x4 v0 = acc[ai][bj][m][0], v1 = acc[ai][bj][m][1];
; #pragma unroll
;                     for (int j = 0; j < 4; ++j) { const float a = fmaxf(v0[j], 0.f), b = fmaxf(v1[j], 0.f); v0[j] = a * a; v1[j] = b * b; }
;                     u32x4 w; w.x = cvt_pk_bf16(v0[0], v0[1]); w.y = cvt_pk_bf16(v0[2], v0[3]); w.z = cvt_pk_bf16(v1[0], v1[1]); w.w = cvt_pk_bf16(v1[2], v1[3]);
;                     *(u32x4*)(rowp + bj * HALF) = w; } }
;     ...
;             PG8_WAIT_V(6); PG8_BAR; PG8_MMA(1, 1, At, B1); PG8_BAR;
;             PG8_LDB(B0, 1, 0); PG8_SCHED; PG8_LDA(At, 1, 0); PG8_STAGE(PG8_SA(0, 1), a2 + hstep, voffA);
;             PG8_WAIT_L(8); PG8_BAR; PG8_WAIT_L(0); PG8_MMA(0, 0, At, B0); PG8_BAR; PG8_SCHED;
;             PG8_LDB(B1, 1, 1); PG8_STAGE(PG8_SB(1, 0), b3, voffB);
;             PG8_BAR; PG8_WAIT_L(0); PG8_MMA(0, 1, At, B1); PG8_BAR;
;             PG8_LDA(At, 1, 1); PG8_STAGE(PG8_SA(1, 0), a3, voffA);
;             PG8_BAR; PG8_WAIT_L(0); PG8_MMA(1, 0, At, B0); PG8_BAR; PG8_SCHED;
;             PG8_STAGE(PG8_SB(1, 1), b3 + hstep, voffB);
;             PG8_WAIT_V(6); PG8_BAR; PG8_MMA(1, 1, At, B1); PG8_BAR;
;         }
	s_waitcnt lgkmcnt(0)
	s_setprio 1
	s_waitcnt lgkmcnt(0)
	v_mfma_f32_16x16x32_bf16 v[60:63], v[140:143], v[160:163], v[60:63]
	v_mfma_f32_16x16x32_bf16 v[56:59], v[152:155], v[160:163], v[56:59]
	v_mfma_f32_16x16x32_bf16 v[44:47], v[140:143], v[168:171], v[44:47]
	v_mfma_f32_16x16x32_bf16 v[40:43], v[152:155], v[168:171], v[40:43]
	v_mfma_f32_16x16x32_bf16 v[28:31], v[140:143], v[176:179], v[28:31]
	v_mfma_f32_16x16x32_bf16 v[24:27], v[152:155], v[176:179], v[24:27]
	v_mfma_f32_16x16x32_bf16 v[12:15], v[140:143], v[184:187], v[12:15]
	v_mfma_f32_16x16x32_bf16 v[8:11], v[152:155], v[184:187], v[8:11]
	v_mfma_f32_16x16x32_bf16 v[60:63], v[148:151], v[164:167], v[60:63]
	v_mfma_f32_16x16x32_bf16 v[56:59], v[156:159], v[164:167], v[56:59]
	v_mfma_f32_16x16x32_bf16 v[44:47], v[148:151], v[172:175], v[44:47]
	v_mfma_f32_16x16x32_bf16 v[40:43], v[156:159], v[172:175], v[40:43]
	v_mfma_f32_16x16x32_bf16 v[28:31], v[148:151], v[180:183], v[28:31]
	v_mfma_f32_16x16x32_bf16 v[24:27], v[156:159], v[180:183], v[24:27]
	v_mfma_f32_16x16x32_bf16 v[12:15], v[148:151], v[188:191], v[12:15]
	v_mfma_f32_16x16x32_bf16 v[8:11], v[156:159], v[188:191], v[8:11]
	s_setprio 0
	s_barrier
	s_add_u32 s2, s12, 0x84080
	s_addc_u32 s3, s13, 0
	s_add_i32 s8, s9, s20
	v_lshl_add_u64 v[140:141], s[2:3], 0, v[64:65]
	s_mov_b32 m0, s8
	s_nop 0
	global_load_lds_dwordx4 v[140:141], off
	v_lshl_add_u64 v[140:141], s[2:3], 0, v[134:135]
	s_add_i32 m0, s8, 0x2000
	s_nop 0
	global_load_lds_dwordx4 v[140:141], off
	s_waitcnt vmcnt(6)
	s_barrier
	s_setprio 1
	v_mfma_f32_16x16x32_bf16 v[52:55], v[192:195], v[160:163], v[52:55]
	v_mfma_f32_16x16x32_bf16 v[48:51], v[220:223], v[160:163], v[48:51]
	v_mfma_f32_16x16x32_bf16 v[36:39], v[192:195], v[168:171], v[36:39]
	v_mfma_f32_16x16x32_bf16 v[32:35], v[220:223], v[168:171], v[32:35]
	v_mfma_f32_16x16x32_bf16 v[20:23], v[192:195], v[176:179], v[20:23]
	v_mfma_f32_16x16x32_bf16 v[16:19], v[220:223], v[176:179], v[16:19]
	v_mfma_f32_16x16x32_bf16 v[4:7], v[192:195], v[184:187], v[4:7]
	v_mfma_f32_16x16x32_bf16 v[0:3], v[220:223], v[184:187], v[0:3]
	v_mfma_f32_16x16x32_bf16 v[52:55], v[196:199], v[164:167], v[52:55]
	v_mfma_f32_16x16x32_bf16 v[48:51], v[224:227], v[164:167], v[48:51]
	v_mfma_f32_16x16x32_bf16 v[36:39], v[196:199], v[172:175], v[36:39]
	v_mfma_f32_16x16x32_bf16 v[32:35], v[224:227], v[172:175], v[32:35]
	v_mfma_f32_16x16x32_bf16 v[20:23], v[196:199], v[180:183], v[20:23]
	v_mfma_f32_16x16x32_bf16 v[16:19], v[224:227], v[180:183], v[16:19]
	v_mfma_f32_16x16x32_bf16 v[4:7], v[196:199], v[188:191], v[4:7]
	v_mfma_f32_16x16x32_bf16 v[0:3], v[224:227], v[188:191], v[0:3]
	s_setprio 0
	s_add_u32 s42, s42, 0x100
	s_addc_u32 s43, s43, 0
	s_cmp_ge_u32 s44, s40
	s_mov_b64 s[8:9], s[10:11]
	s_mov_b32 s2, s44
	s_barrier
	s_cbranch_scc0 .LBB0_120
	v_max_f32_e32 v122, 0, v122
	v_lshl_or_b32 v142, s37, 8, v146
	v_mul_f32_e32 v151, v122, v122
	v_max_f32_e32 v122, v127, v127
	v_max_f32_e32 v123, 0, v123
	v_max_f32_e32 v124, 0, v124
	v_lshl_add_u32 v150, s38, 8, v144
	v_ashrrev_i32_e32 v143, 31, v142
	v_mov_b64_e32 v[140:141], s[80:81]
	s_movk_i32 s8, 0x4080
	v_max_f32_e32 v122, 0, v122
	v_mul_f32_e32 v127, v123, v123
	v_max_f32_e32 v123, v128, v128
	v_mul_f32_e32 v128, v124, v124
	v_max_f32_e32 v124, v129, v129
	v_mad_i64_i32 v[148:149], s[2:3], v150, s8, v[140:141]
	v_lshlrev_b64 v[142:143], 1, v[142:143]
	v_max_f32_e32 v126, 0, v126
	v_mul_f32_e32 v122, v122, v122
	v_max_f32_e32 v123, 0, v123
	v_max_f32_e32 v124, 0, v124
	v_max_f32_e32 v125, 0, v125
	v_lshl_add_u64 v[148:149], v[148:149], 0, v[142:143]
	v_mul_f32_e32 v126, v126, v126
	v_mul_f32_e32 v123, v123, v123
	v_mul_f32_e32 v124, v124, v124
	v_mul_f32_e32 v125, v125, v125
	v_cvt_pk_bf16_f32 v122, v126, v122
	v_max_f32_e32 v114, 0, v114
	v_max_f32_e32 v115, 0, v115
	v_max_f32_e32 v116, 0, v116
	v_cvt_pk_bf16_f32 v123, v123, v124
	v_cvt_pk_bf16_f32 v124, v151, v127
	v_cvt_pk_bf16_f32 v125, v128, v125
	global_store_dwordx4 v[148:149], v[122:125], off
	s_nop 1
	v_mul_f32_e32 v122, v114, v114
	v_max_f32_e32 v114, v119, v119
	v_mul_f32_e32 v119, v115, v115
	v_max_f32_e32 v115, v120, v120
	v_mul_f32_e32 v120, v116, v116
	v_max_f32_e32 v116, v121, v121
	v_max_f32_e32 v114, 0, v114
	v_max_f32_e32 v115, 0, v115
	v_max_f32_e32 v116, 0, v116
	v_max_f32_e32 v118, 0, v118
	v_mul_f32_e32 v114, v114, v114
	v_mul_f32_e32 v115, v115, v115
	v_max_f32_e32 v117, 0, v117
	v_mul_f32_e32 v116, v116, v116
	v_mul_f32_e32 v118, v118, v118
	v_mul_f32_e32 v117, v117, v117
	v_cvt_pk_bf16_f32 v114, v118, v114
	v_cvt_pk_bf16_f32 v115, v115, v116
	v_cvt_pk_bf16_f32 v116, v122, v119
	v_max_f32_e32 v106, 0, v106
	v_cvt_pk_bf16_f32 v117, v120, v117
	global_store_dwordx4 v[148:149], v[114:117], off offset:256
	s_nop 1
	v_max_f32_e32 v107, 0, v107
	v_max_f32_e32 v108, 0, v108
	v_mul_f32_e32 v116, v106, v106
	v_max_f32_e32 v106, v111, v111
	v_or_b32_e32 v114, 16, v150
	v_max_f32_e32 v106, 0, v106
	v_mul_f32_e32 v111, v107, v107
	v_max_f32_e32 v107, v112, v112
	v_mul_f32_e32 v112, v108, v108
	v_max_f32_e32 v108, v113, v113
	v_mad_i64_i32 v[114:115], s[2:3], v114, s8, v[140:141]
	v_max_f32_e32 v110, 0, v110
	v_mul_f32_e32 v106, v106, v106
	v_max_f32_e32 v107, 0, v107
	v_max_f32_e32 v108, 0, v108
	v_max_f32_e32 v109, 0, v109
	v_lshl_add_u64 v[114:115], v[114:115], 0, v[142:143]
	v_mul_f32_e32 v110, v110, v110
	v_mul_f32_e32 v107, v107, v107
	v_mul_f32_e32 v108, v108, v108
	v_mul_f32_e32 v109, v109, v109
	v_cvt_pk_bf16_f32 v106, v110, v106
	v_max_f32_e32 v98, 0, v98
	v_max_f32_e32 v99, 0, v99
	v_max_f32_e32 v100, 0, v100
	v_cvt_pk_bf16_f32 v107, v107, v108
	v_cvt_pk_bf16_f32 v108, v116, v111
	v_cvt_pk_bf16_f32 v109, v112, v109
; __device__ __forceinline__ unsigned cvt_pk_bf16(float lo, float hi) { unsigned r; asm volatile("v_cvt_pk_bf16_f32 %0, %1, %2" : "=v"(r) : "v"(lo), "v"(hi)); return r; }
;     __device__ __forceinline__ void operator()(const f32x4 (&acc)[2][2][4][2], const Unit& u, int wr, int wc, int fr, int fq) const {
;     ...
;             for (int m = 0; m < 4; ++m) { bf16_t* rowp = O + (size_t)(row0 + ai * HALF + m * 16) * LDF + col0;
; #pragma unroll
;                 for (int bj = 0; bj < 2; ++bj) { f32x4 v0 = acc[ai][bj][m][0], v1 = acc[ai][bj][m][1];
; #pragma unroll
;                     for (int j = 0; j < 4; ++j) { const float a = fmaxf(v0[j], 0.f), b = fmaxf(v1[j], 0.f); v0[j] = a * a; v1[j] = b * b; }
;                     u32x4 w; w.x = cvt_pk_bf16(v0[0], v0[1]); w.y = cvt_pk_bf16(v0[2], v0[3]); w.z = cvt_pk_bf16(v1[0], v1[1]); w.w = cvt_pk_bf16(v1[2], v1[3]);
;                     *(u32x4*)(rowp + bj * HALF) = w; } }
	global_store_dwordx4 v[114:115], v[106:109], off
	s_nop 1
	v_mul_f32_e32 v106, v98, v98
	v_max_f32_e32 v98, v103, v103
	v_mul_f32_e32 v103, v99, v99
	v_max_f32_e32 v99, v104, v104
	v_mul_f32_e32 v104, v100, v100
	v_max_f32_e32 v100, v105, v105
	v_max_f32_e32 v98, 0, v98
	v_max_f32_e32 v99, 0, v99
	v_max_f32_e32 v100, 0, v100
	v_max_f32_e32 v102, 0, v102
	v_mul_f32_e32 v98, v98, v98
	v_mul_f32_e32 v99, v99, v99
	v_max_f32_e32 v101, 0, v101
	v_mul_f32_e32 v100, v100, v100
	v_mul_f32_e32 v102, v102, v102
	v_mul_f32_e32 v101, v101, v101
	v_cvt_pk_bf16_f32 v98, v102, v98
	v_cvt_pk_bf16_f32 v99, v99, v100
	v_cvt_pk_bf16_f32 v100, v106, v103
	v_max_f32_e32 v90, 0, v90
	v_cvt_pk_bf16_f32 v101, v104, v101
	global_store_dwordx4 v[114:115], v[98:101], off offset:256
	s_nop 1
	v_max_f32_e32 v91, 0, v91
	v_max_f32_e32 v92, 0, v92
	v_mul_f32_e32 v100, v90, v90
	v_max_f32_e32 v90, v95, v95
	v_or_b32_e32 v98, 32, v150
	v_max_f32_e32 v90, 0, v90
	v_mul_f32_e32 v95, v91, v91
	v_max_f32_e32 v91, v96, v96
	v_mul_f32_e32 v96, v92, v92
	v_max_f32_e32 v92, v97, v97
	v_mad_i64_i32 v[98:99], s[2:3], v98, s8, v[140:141]
	v_max_f32_e32 v94, 0, v94
	v_mul_f32_e32 v90, v90, v90
	v_max_f32_e32 v91, 0, v91
	v_max_f32_e32 v92, 0, v92
	v_max_f32_e32 v93, 0, v93
	v_lshl_add_u64 v[98:99], v[98:99], 0, v[142:143]
	v_mul_f32_e32 v94, v94, v94
	v_mul_f32_e32 v91, v91, v91
	v_mul_f32_e32 v92, v92, v92
	v_mul_f32_e32 v93, v93, v93
	v_cvt_pk_bf16_f32 v90, v94, v90
	v_max_f32_e32 v82, 0, v82
	v_max_f32_e32 v83, 0, v83
	v_max_f32_e32 v84, 0, v84
	v_cvt_pk_bf16_f32 v91, v91, v92
	v_cvt_pk_bf16_f32 v92, v100, v95
	v_cvt_pk_bf16_f32 v93, v96, v93
	global_store_dwordx4 v[98:99], v[90:93], off
	s_nop 1
	v_mul_f32_e32 v90, v82, v82
	v_max_f32_e32 v82, v87, v87
	v_mul_f32_e32 v87, v83, v83
	v_max_f32_e32 v83, v88, v88
	v_mul_f32_e32 v88, v84, v84
	v_max_f32_e32 v84, v89, v89
	v_max_f32_e32 v82, 0, v82
	v_max_f32_e32 v83, 0, v83
	v_max_f32_e32 v84, 0, v84
	v_max_f32_e32 v86, 0, v86
	v_mul_f32_e32 v82, v82, v82
	v_mul_f32_e32 v83, v83, v83
	v_max_f32_e32 v85, 0, v85
	v_mul_f32_e32 v84, v84, v84
	v_mul_f32_e32 v86, v86, v86
	v_mul_f32_e32 v85, v85, v85
	v_cvt_pk_bf16_f32 v82, v86, v82
	v_cvt_pk_bf16_f32 v83, v83, v84
	v_cvt_pk_bf16_f32 v84, v90, v87
	v_max_f32_e32 v74, 0, v74
	v_cvt_pk_bf16_f32 v85, v88, v85
	global_store_dwordx4 v[98:99], v[82:85], off offset:256
	s_nop 1
	v_max_f32_e32 v75, 0, v75
	v_max_f32_e32 v76, 0, v76
	v_mul_f32_e32 v84, v74, v74
	v_max_f32_e32 v74, v79, v79
	v_or_b32_e32 v82, 48, v150
	v_max_f32_e32 v74, 0, v74
	v_mul_f32_e32 v79, v75, v75
	v_max_f32_e32 v75, v80, v80
	v_mul_f32_e32 v80, v76, v76
	v_max_f32_e32 v76, v81, v81
	v_mad_i64_i32 v[82:83], s[2:3], v82, s8, v[140:141]
	v_max_f32_e32 v78, 0, v78
	v_mul_f32_e32 v74, v74, v74
	v_max_f32_e32 v75, 0, v75
	v_max_f32_e32 v76, 0, v76
	v_max_f32_e32 v77, 0, v77
	v_lshl_add_u64 v[82:83], v[82:83], 0, v[142:143]
	v_mul_f32_e32 v78, v78, v78
	v_mul_f32_e32 v75, v75, v75
	v_mul_f32_e32 v76, v76, v76
	v_mul_f32_e32 v77, v77, v77
	v_cvt_pk_bf16_f32 v74, v78, v74
	v_max_f32_e32 v66, 0, v66
	v_max_f32_e32 v67, 0, v67
	v_max_f32_e32 v68, 0, v68
	v_cvt_pk_bf16_f32 v75, v75, v76
	v_cvt_pk_bf16_f32 v76, v84, v79
	v_cvt_pk_bf16_f32 v77, v80, v77
	global_store_dwordx4 v[82:83], v[74:77], off
	s_nop 1
	v_mul_f32_e32 v74, v66, v66
	v_max_f32_e32 v66, v71, v71
	v_mul_f32_e32 v71, v67, v67
	v_max_f32_e32 v67, v72, v72
	v_mul_f32_e32 v72, v68, v68
	v_max_f32_e32 v68, v73, v73
	v_max_f32_e32 v66, 0, v66
	v_max_f32_e32 v67, 0, v67
	v_max_f32_e32 v68, 0, v68
	v_max_f32_e32 v70, 0, v70
	v_mul_f32_e32 v66, v66, v66
	v_mul_f32_e32 v67, v67, v67
	v_max_f32_e32 v69, 0, v69
	v_mul_f32_e32 v68, v68, v68
	v_mul_f32_e32 v70, v70, v70
	v_mul_f32_e32 v69, v69, v69
	v_cvt_pk_bf16_f32 v66, v70, v66
	v_cvt_pk_bf16_f32 v67, v67, v68
	v_cvt_pk_bf16_f32 v68, v74, v71
	v_max_f32_e32 v56, 0, v56
	v_cvt_pk_bf16_f32 v69, v72, v69
	global_store_dwordx4 v[82:83], v[66:69], off offset:256
	s_nop 1
	v_max_f32_e32 v57, 0, v57
	v_max_f32_e32 v58, 0, v58
	v_mul_f32_e32 v68, v56, v56
	v_max_f32_e32 v56, v61, v61
	v_add_u32_e32 v66, 0x80, v150
	v_max_f32_e32 v56, 0, v56
	v_mul_f32_e32 v61, v57, v57
	v_max_f32_e32 v57, v62, v62
	v_mul_f32_e32 v62, v58, v58
	v_max_f32_e32 v58, v63, v63
	v_mad_i64_i32 v[66:67], s[2:3], v66, s8, v[140:141]
	v_max_f32_e32 v60, 0, v60
	v_mul_f32_e32 v56, v56, v56
	v_max_f32_e32 v57, 0, v57
	v_max_f32_e32 v58, 0, v58
	v_max_f32_e32 v59, 0, v59
	v_lshl_add_u64 v[66:67], v[66:67], 0, v[142:143]
	v_mul_f32_e32 v60, v60, v60
	v_mul_f32_e32 v57, v57, v57
	v_mul_f32_e32 v58, v58, v58
	v_mul_f32_e32 v59, v59, v59
	v_cvt_pk_bf16_f32 v56, v60, v56
	v_max_f32_e32 v48, 0, v48
	v_max_f32_e32 v49, 0, v49
	v_max_f32_e32 v50, 0, v50
	v_cvt_pk_bf16_f32 v57, v57, v58
	v_cvt_pk_bf16_f32 v58, v68, v61
	v_cvt_pk_bf16_f32 v59, v62, v59
	global_store_dwordx4 v[66:67], v[56:59], off
	s_nop 1
	v_mul_f32_e32 v56, v48, v48
	v_max_f32_e32 v48, v53, v53
	v_mul_f32_e32 v53, v49, v49
	v_max_f32_e32 v49, v54, v54
	v_mul_f32_e32 v54, v50, v50
	v_max_f32_e32 v50, v55, v55
	v_max_f32_e32 v48, 0, v48
	v_max_f32_e32 v49, 0, v49
	v_max_f32_e32 v50, 0, v50
	v_max_f32_e32 v52, 0, v52
	v_mul_f32_e32 v48, v48, v48
	v_mul_f32_e32 v49, v49, v49
	v_max_f32_e32 v51, 0, v51
	v_mul_f32_e32 v50, v50, v50
	v_mul_f32_e32 v52, v52, v52
	v_mul_f32_e32 v51, v51, v51
; __device__ __forceinline__ unsigned cvt_pk_bf16(float lo, float hi) { unsigned r; asm volatile("v_cvt_pk_bf16_f32 %0, %1, %2" : "=v"(r) : "v"(lo), "v"(hi)); return r; }
;     __device__ __forceinline__ void operator()(const f32x4 (&acc)[2][2][4][2], const Unit& u, int wr, int wc, int fr, int fq) const {
;     ...
;             for (int m = 0; m < 4; ++m) { bf16_t* rowp = O + (size_t)(row0 + ai * HALF + m * 16) * LDF + col0;
; #pragma unroll
;                 for (int bj = 0; bj < 2; ++bj) { f32x4 v0 = acc[ai][bj][m][0], v1 = acc[ai][bj][m][1];
; #pragma unroll
;                     for (int j = 0; j < 4; ++j) { const float a = fmaxf(v0[j], 0.f), b = fmaxf(v1[j], 0.f); v0[j] = a * a; v1[j] = b * b; }
;                     u32x4 w; w.x = cvt_pk_bf16(v0[0], v0[1]); w.y = cvt_pk_bf16(v0[2], v0[3]); w.z = cvt_pk_bf16(v1[0], v1[1]); w.w = cvt_pk_bf16(v1[2], v1[3]);
;                     *(u32x4*)(rowp + bj * HALF) = w; } }
;     ...
;         if (!has_next) break;
; #pragma unroll
;         for (int a = 0; a < 2; ++a)
; #pragma unroll
;             for (int b = 0; b < 2; ++b)
; #pragma unroll
;                 for (int m = 0; m < 4; ++m)
; #pragma unroll
;                     for (int n = 0; n < 2; ++n) acc[a][b][m][n] = (f32x4){0.f, 0.f, 0.f, 0.f};
;         cur = nxt; cA = nA; cB = nB; ++ui;
	v_cvt_pk_bf16_f32 v48, v52, v48
	v_cvt_pk_bf16_f32 v49, v49, v50
	v_cvt_pk_bf16_f32 v50, v56, v53
	v_max_f32_e32 v40, 0, v40
	v_cvt_pk_bf16_f32 v51, v54, v51
	global_store_dwordx4 v[66:67], v[48:51], off offset:256
	s_nop 1
	v_max_f32_e32 v41, 0, v41
	v_max_f32_e32 v42, 0, v42
	v_mul_f32_e32 v50, v40, v40
	v_max_f32_e32 v40, v45, v45
	v_add_u32_e32 v48, 0x90, v150
	v_max_f32_e32 v40, 0, v40
	v_mul_f32_e32 v45, v41, v41
	v_max_f32_e32 v41, v46, v46
	v_mul_f32_e32 v46, v42, v42
	v_max_f32_e32 v42, v47, v47
	v_mad_i64_i32 v[48:49], s[2:3], v48, s8, v[140:141]
	v_max_f32_e32 v44, 0, v44
	v_mul_f32_e32 v40, v40, v40
	v_max_f32_e32 v41, 0, v41
	v_max_f32_e32 v42, 0, v42
	v_max_f32_e32 v43, 0, v43
	v_lshl_add_u64 v[48:49], v[48:49], 0, v[142:143]
	v_mul_f32_e32 v44, v44, v44
	v_mul_f32_e32 v41, v41, v41
	v_mul_f32_e32 v42, v42, v42
	v_mul_f32_e32 v43, v43, v43
	v_cvt_pk_bf16_f32 v40, v44, v40
	v_max_f32_e32 v32, 0, v32
	v_max_f32_e32 v33, 0, v33
	v_max_f32_e32 v34, 0, v34
	v_cvt_pk_bf16_f32 v41, v41, v42
	v_cvt_pk_bf16_f32 v42, v50, v45
	v_cvt_pk_bf16_f32 v43, v46, v43
	global_store_dwordx4 v[48:49], v[40:43], off
	s_nop 1
	v_mul_f32_e32 v40, v32, v32
	v_max_f32_e32 v32, v37, v37
	v_mul_f32_e32 v37, v33, v33
	v_max_f32_e32 v33, v38, v38
	v_mul_f32_e32 v38, v34, v34
	v_max_f32_e32 v34, v39, v39
	v_max_f32_e32 v32, 0, v32
	v_max_f32_e32 v33, 0, v33
	v_max_f32_e32 v34, 0, v34
	v_max_f32_e32 v36, 0, v36
	v_mul_f32_e32 v32, v32, v32
	v_mul_f32_e32 v33, v33, v33
	v_max_f32_e32 v35, 0, v35
	v_mul_f32_e32 v34, v34, v34
	v_mul_f32_e32 v36, v36, v36
	v_mul_f32_e32 v35, v35, v35
	v_cvt_pk_bf16_f32 v32, v36, v32
	v_cvt_pk_bf16_f32 v33, v33, v34
	v_cvt_pk_bf16_f32 v34, v40, v37
	v_max_f32_e32 v24, 0, v24
	v_cvt_pk_bf16_f32 v35, v38, v35
	global_store_dwordx4 v[48:49], v[32:35], off offset:256
	s_nop 1
	v_max_f32_e32 v25, 0, v25
	v_max_f32_e32 v26, 0, v26
	v_mul_f32_e32 v34, v24, v24
	v_max_f32_e32 v24, v29, v29
	v_add_u32_e32 v32, 0xa0, v150
	v_max_f32_e32 v24, 0, v24
	v_mul_f32_e32 v29, v25, v25
	v_max_f32_e32 v25, v30, v30
	v_mul_f32_e32 v30, v26, v26
	v_max_f32_e32 v26, v31, v31
	v_mad_i64_i32 v[32:33], s[2:3], v32, s8, v[140:141]
	v_max_f32_e32 v28, 0, v28
	v_mul_f32_e32 v24, v24, v24
	v_max_f32_e32 v25, 0, v25
	v_max_f32_e32 v26, 0, v26
	v_max_f32_e32 v27, 0, v27
	v_lshl_add_u64 v[32:33], v[32:33], 0, v[142:143]
	v_mul_f32_e32 v28, v28, v28
	v_mul_f32_e32 v25, v25, v25
	v_mul_f32_e32 v26, v26, v26
	v_mul_f32_e32 v27, v27, v27
	v_cvt_pk_bf16_f32 v24, v28, v24
	v_max_f32_e32 v16, 0, v16
	v_max_f32_e32 v17, 0, v17
	v_max_f32_e32 v18, 0, v18
	v_cvt_pk_bf16_f32 v25, v25, v26
	v_cvt_pk_bf16_f32 v26, v34, v29
	v_cvt_pk_bf16_f32 v27, v30, v27
	global_store_dwordx4 v[32:33], v[24:27], off
	s_nop 1
	v_mul_f32_e32 v24, v16, v16
	v_max_f32_e32 v16, v21, v21
	v_mul_f32_e32 v21, v17, v17
	v_max_f32_e32 v17, v22, v22
	v_mul_f32_e32 v22, v18, v18
	v_max_f32_e32 v18, v23, v23
	v_max_f32_e32 v16, 0, v16
	v_max_f32_e32 v17, 0, v17
	v_max_f32_e32 v18, 0, v18
	v_max_f32_e32 v20, 0, v20
	v_mul_f32_e32 v16, v16, v16
	v_mul_f32_e32 v17, v17, v17
	v_max_f32_e32 v19, 0, v19
	v_mul_f32_e32 v18, v18, v18
	v_mul_f32_e32 v20, v20, v20
	v_mul_f32_e32 v19, v19, v19
	v_cvt_pk_bf16_f32 v16, v20, v16
	v_cvt_pk_bf16_f32 v17, v17, v18
	v_cvt_pk_bf16_f32 v18, v24, v21
	v_max_f32_e32 v8, 0, v8
	v_cvt_pk_bf16_f32 v19, v22, v19
	global_store_dwordx4 v[32:33], v[16:19], off offset:256
	s_nop 1
	v_max_f32_e32 v9, 0, v9
	v_max_f32_e32 v10, 0, v10
	v_mul_f32_e32 v18, v8, v8
	v_max_f32_e32 v8, v13, v13
	v_add_u32_e32 v16, 0xb0, v150
	v_max_f32_e32 v8, 0, v8
	v_mul_f32_e32 v13, v9, v9
	v_max_f32_e32 v9, v14, v14
	v_mul_f32_e32 v14, v10, v10
	v_max_f32_e32 v10, v15, v15
	v_mad_i64_i32 v[16:17], s[2:3], v16, s8, v[140:141]
	v_max_f32_e32 v12, 0, v12
	v_mul_f32_e32 v8, v8, v8
	v_max_f32_e32 v9, 0, v9
	v_max_f32_e32 v10, 0, v10
	v_max_f32_e32 v11, 0, v11
	v_lshl_add_u64 v[16:17], v[16:17], 0, v[142:143]
	v_mul_f32_e32 v12, v12, v12
	v_mul_f32_e32 v9, v9, v9
	v_mul_f32_e32 v10, v10, v10
	v_mul_f32_e32 v11, v11, v11
	v_cvt_pk_bf16_f32 v8, v12, v8
	v_max_f32_e32 v0, 0, v0
	v_max_f32_e32 v1, 0, v1
	v_max_f32_e32 v2, 0, v2
	v_cvt_pk_bf16_f32 v9, v9, v10
	v_cvt_pk_bf16_f32 v10, v18, v13
	v_cvt_pk_bf16_f32 v11, v14, v11
	global_store_dwordx4 v[16:17], v[8:11], off
	s_nop 1
	v_mul_f32_e32 v8, v0, v0
	v_max_f32_e32 v0, v5, v5
	v_mul_f32_e32 v5, v1, v1
	v_max_f32_e32 v1, v6, v6
	v_mul_f32_e32 v6, v2, v2
	v_max_f32_e32 v2, v7, v7
	v_max_f32_e32 v0, 0, v0
	v_max_f32_e32 v1, 0, v1
	v_max_f32_e32 v2, 0, v2
	v_max_f32_e32 v3, 0, v3
	v_max_f32_e32 v4, 0, v4
	v_mul_f32_e32 v0, v0, v0
	v_mul_f32_e32 v1, v1, v1
	v_mul_f32_e32 v2, v2, v2
	v_mul_f32_e32 v3, v3, v3
	s_and_b64 vcc, exec, s[4:5]
	s_mov_b32 s38, s34
	s_mov_b32 s37, s36
	s_mov_b32 s40, s39
	s_mov_b64 s[10:11], s[18:19]
	s_mov_b64 s[8:9], s[6:7]
	s_mov_b32 s18, s33
	v_readlane_b32 s35, v251, 41
	v_mul_f32_e32 v4, v4, v4
	v_cvt_pk_bf16_f32 v0, v4, v0
	v_cvt_pk_bf16_f32 v1, v1, v2
	v_cvt_pk_bf16_f32 v2, v8, v5
	v_cvt_pk_bf16_f32 v3, v6, v3
	global_store_dwordx4 v[16:17], v[0:3], off offset:256
	s_nop 1
	s_cbranch_vccz .LBB0_96
	s_waitcnt vmcnt(0)
	v_readlane_b32 s40, v251, 24
	v_readlane_b32 s28, v252, 58
	s_cmpk_gt_u32 s15, 0xff
	s_movk_i32 s27, 0x1000
	v_readlane_b32 s41, v251, 25
	v_readlane_b32 s29, v252, 59
	s_cbranch_scc1 .LBB0_124
	s_barrier

; __device__ __forceinline__ void ln_phase(const bf16_t* Y, const bf16_t* YP, const float* g, const float* b, float* of, bf16_t* ob, const int row_begin, const int row_stride, const int nwaves, const int nparts) {
;     ...
;     for (int row = row_begin + wid; row < MT; row += row_stride) {
;         f32x4 v[8]; float s = 0.f;
;         if (YP != nullptr && row >= MP) {
;             const bf16_t* pp = YP + (size_t)(row - MP) * DM + lane * 8;
; #pragma unroll
;             for (int i = 0; i < 8; ++i) v[i] = (f32x4){0.f, 0.f, 0.f, 0.f};
; #pragma unroll 1
;             for (int sb = 0; sb < nparts; sb += 4) {
;                 u32x4 raw[4][4];
; #pragma unroll
;                 for (int s4 = 0; s4 < 4; ++s4)
; #pragma unroll
;                     for (int i = 0; i < 4; ++i) raw[s4][i] = *(const u32x4*)(pp + (size_t)(sb + s4) * MS * DM + i * 512);
; #pragma unroll
;                 for (int s4 = 0; s4 < 4; ++s4)
; #pragma unroll
;                     for (int i = 0; i < 4; ++i) { f32x4 a, c; unpack8(raw[s4][i], a, c); v[2 * i] += a; v[2 * i + 1] += c; }
;             }
;         } else {
; #pragma unroll
;             for (int i = 0; i < 4; ++i) unpack8(*(const u32x4*)(Y + (size_t)row * DM + i * 512 + lane * 8), v[2 * i], v[2 * i + 1]);
;         }
; #pragma unroll
;         for (int i = 0; i < 8; ++i) s += (v[i][0] + v[i][1]) + (v[i][2] + v[i][3]);
; #pragma unroll
;         for (int o = 32; o >= 1; o >>= 1) s += __shfl_xor(s, o);
;         const float mean = s * (1.0f / 2048.0f); float q = 0.f;
; #pragma unroll
;         for (int i = 0; i < 8; ++i) { const f32x4 d = v[i] - mean; q += (d[0] * d[0] + d[1] * d[1]) + (d[2] * d[2] + d[3] * d[3]); }
; #pragma unroll
;         for (int o = 32; o >= 1; o >>= 1) q += __shfl_xor(q, o);
;         const float rstd = rsqrtf(q * (1.0f / 2048.0f) + LN_EPS);
.LBB0_131:
	v_lshl_add_u64 v[0:1], v[20:21], 0, v[64:65]
	v_add_co_u32_e32 v22, vcc, 0x269a1000, v0
	s_mov_b32 s2, 0x18d20000
	s_nop 0
	v_addc_co_u32_e32 v23, vcc, 0, v1, vcc
	global_load_dwordx4 v[0:3], v[22:23], off
	global_load_dwordx4 v[52:55], v[22:23], off offset:1024
	v_add_u32_e32 v4, s36, v4
	v_lshl_add_u64 v[20:21], v[20:21], 0, s[40:41]
	global_load_dwordx4 v[28:31], v[22:23], off offset:3072
	s_waitcnt vmcnt(0)
	v_and_b32_e32 v59, 0xffff0000, v0
	v_lshlrev_b32_e32 v44, 16, v54
	v_and_b32_e32 v45, 0xffff0000, v54
	v_lshlrev_b32_e32 v46, 16, v55
	v_and_b32_e32 v47, 0xffff0000, v55
	global_load_dwordx4 v[54:57], v[22:23], off offset:2048
	v_and_b32_e32 v58, 0xffff0000, v2
	v_lshlrev_b32_e32 v69, 16, v1
	v_lshlrev_b32_e32 v68, 16, v3
	v_and_b32_e32 v71, 0xffff0000, v1
	v_and_b32_e32 v70, 0xffff0000, v3
	v_lshlrev_b32_e32 v51, 16, v53
	v_lshlrev_b32_e32 v50, 16, v52
	v_and_b32_e32 v53, 0xffff0000, v53
	v_and_b32_e32 v52, 0xffff0000, v52
	v_add_f32_e32 v39, v44, v45
	v_add_f32_e32 v41, v46, v47
	v_lshlrev_b32_e32 v26, 16, v28
	v_and_b32_e32 v27, 0xffff0000, v28
	v_lshlrev_b32_e32 v28, 16, v29
	v_and_b32_e32 v29, 0xffff0000, v29
	v_lshlrev_b32_e32 v24, 16, v30
	v_and_b32_e32 v32, 0xffff0000, v30
	v_lshlrev_b32_e32 v22, 16, v31
	v_and_b32_e32 v30, 0xffff0000, v31
	v_add_f32_e32 v25, v26, v27
	v_add_f32_e32 v33, v28, v29
	s_waitcnt vmcnt(0)
	v_lshlrev_b32_e32 v38, 16, v54
	v_and_b32_e32 v40, 0xffff0000, v54
	v_lshlrev_b32_e32 v34, 16, v55
	v_and_b32_e32 v36, 0xffff0000, v55
	v_lshlrev_b32_e32 v55, 16, v0
	v_lshlrev_b32_e32 v54, 16, v2
	v_pk_add_f32 v[0:1], v[54:55], v[58:59]
	v_pk_add_f32 v[2:3], v[68:69], v[70:71]
	v_lshlrev_b32_e32 v43, 16, v57
	v_pk_add_f32 v[0:1], v[0:1], v[2:3]
	v_pk_add_f32 v[2:3], v[38:39], v[40:41]
	v_add_f32_e32 v1, 0, v1
	v_add_f32_e32 v37, v0, v1
	v_pk_add_f32 v[0:1], v[50:51], v[52:53]
	v_lshlrev_b32_e32 v42, 16, v56
	v_pk_add_f32 v[0:1], v[0:1], v[0:1] op_sel_hi:[0,1]
	v_mov_b32_e32 v35, v1
	v_pk_add_f32 v[0:1], v[34:35], v[36:37]
	v_and_b32_e32 v73, 0xffff0000, v57
	v_and_b32_e32 v72, 0xffff0000, v56
	v_pk_add_f32 v[0:1], v[2:3], v[0:1]
	v_pk_add_f32 v[2:3], v[42:43], v[72:73]
	v_pk_add_f32 v[0:1], v[0:1], v[0:1] op_sel_hi:[0,1]
	v_pk_add_f32 v[2:3], v[2:3], v[2:3] op_sel_hi:[0,1]
	v_mov_b32_e32 v23, v3
	v_mov_b32_e32 v31, v1
	v_pk_add_f32 v[56:57], v[24:25], v[32:33]
	v_pk_add_f32 v[0:1], v[22:23], v[30:31]
	s_nop 0
	v_pk_add_f32 v[0:1], v[56:57], v[0:1]
	s_nop 0
	v_add_f32_e32 v0, v0, v1
	ds_bpermute_b32 v1, v49, v0
	s_waitcnt lgkmcnt(0)
	v_add_f32_e32 v0, v0, v1
	ds_bpermute_b32 v1, v60, v0
	s_waitcnt lgkmcnt(0)
	v_add_f32_e32 v0, v0, v1
	ds_bpermute_b32 v1, v61, v0
	s_waitcnt lgkmcnt(0)
	v_add_f32_e32 v0, v0, v1
	ds_bpermute_b32 v1, v62, v0
	s_waitcnt lgkmcnt(0)
	v_add_f32_e32 v0, v0, v1
	ds_bpermute_b32 v1, v63, v0
	s_waitcnt lgkmcnt(0)
	v_add_f32_e32 v0, v0, v1
	ds_bpermute_b32 v1, v66, v0
	s_waitcnt lgkmcnt(0)
	v_add_f32_e32 v5, v0, v1
	v_fmac_f32_e32 v59, 0xba000000, v5
	v_fmac_f32_e32 v55, 0xba000000, v5
	v_fmac_f32_e32 v58, 0xba000000, v5
	v_fmac_f32_e32 v54, 0xba000000, v5
	v_mov_b32_e32 v0, v54
	v_mov_b32_e32 v2, v55
	v_mov_b32_e32 v56, v55
	v_mov_b32_e32 v57, v54
	v_mov_b32_e32 v54, v59
	v_mov_b32_e32 v55, v58
	v_fmac_f32_e32 v71, 0xba000000, v5
	v_fmac_f32_e32 v69, 0xba000000, v5
	v_fmac_f32_e32 v70, 0xba000000, v5
	v_fmac_f32_e32 v68, 0xba000000, v5
	v_pk_mul_f32 v[54:55], v[54:55], v[54:55]
	v_mov_b32_e32 v1, v58
	v_pk_fma_f32 v[54:55], v[56:57], v[56:57], v[54:55]
	v_mov_b32_e32 v56, v68
	v_mov_b32_e32 v58, v69
	v_mov_b32_e32 v74, v69
	v_mov_b32_e32 v75, v68
	v_mov_b32_e32 v68, v71
	v_mov_b32_e32 v69, v70
	v_pk_mul_f32 v[68:69], v[68:69], v[68:69]
	v_fmac_f32_e32 v52, 0xba000000, v5
	v_pk_fma_f32 v[68:69], v[74:75], v[74:75], v[68:69]
	v_fmac_f32_e32 v53, 0xba000000, v5
	v_pk_add_f32 v[54:55], v[54:55], v[68:69]
	v_fmac_f32_e32 v51, 0xba000000, v5
	v_pk_add_f32 v[68:69], v[54:55], v[54:55] op_sel_hi:[0,1]
	v_fmac_f32_e32 v50, 0xba000000, v5
	v_mov_b32_e32 v54, v51
	v_mov_b32_e32 v55, v53
	v_mov_b32_e32 v51, v52
	v_mov_b32_e32 v3, v59
	v_mov_b32_e32 v57, v70
	v_mov_b32_e32 v59, v71
	v_pk_mul_f32 v[70:71], v[54:55], v[54:55]
	v_pk_mul_f32 v[52:53], v[50:51], v[50:51]
	v_fmac_f32_e32 v44, 0xba000000, v5
	v_pk_mov_b32 v[74:75], v[52:53], v[70:71] op_sel:[1,0]
	v_mov_b32_e32 v53, v71
	v_fmac_f32_e32 v45, 0xba000000, v5
	v_fmac_f32_e32 v46, 0xba000000, v5
	v_mul_f32_e32 v48, v44, v44
	v_pk_add_f32 v[52:53], v[74:75], v[52:53]
	v_fmac_f32_e32 v47, 0xba000000, v5
	v_pk_fma_f32 v[70:71], v[44:45], v[44:45], v[48:49] op_sel_hi:[1,1,0]
	v_mul_f32_e32 v48, v46, v46
	v_pk_add_f32 v[52:53], v[52:53], v[52:53] op_sel_hi:[0,1]
	v_pk_fma_f32 v[74:75], v[46:47], v[46:47], v[48:49] op_sel_hi:[1,1,0]
	v_fmac_f32_e32 v36, 0xba000000, v5
	v_fmac_f32_e32 v34, 0xba000000, v5
	v_fmac_f32_e32 v40, 0xba000000, v5
	v_fmac_f32_e32 v38, 0xba000000, v5
	v_mul_f32_e32 v70, v38, v38
	v_mul_f32_e32 v74, v40, v40
	v_mul_f32_e32 v52, v34, v34
	v_mul_f32_e32 v68, v36, v36
	v_pk_add_f32 v[70:71], v[70:71], v[74:75]
	v_pk_add_f32 v[52:53], v[52:53], v[68:69]
	v_fmac_f32_e32 v72, 0xba000000, v5
	v_fmac_f32_e32 v73, 0xba000000, v5
	v_fmac_f32_e32 v43, 0xba000000, v5
	v_pk_add_f32 v[68:69], v[70:71], v[52:53]
	v_fmac_f32_e32 v42, 0xba000000, v5
	v_mov_b32_e32 v52, v43
	v_mov_b32_e32 v53, v73
	v_mov_b32_e32 v43, v72
	v_pk_mul_f32 v[70:71], v[52:53], v[52:53]
	v_pk_mul_f32 v[72:73], v[42:43], v[42:43]
	v_fmac_f32_e32 v32, 0xba000000, v5
	v_pk_mov_b32 v[74:75], v[72:73], v[70:71] op_sel:[1,0]
	v_mov_b32_e32 v73, v71
	v_pk_add_f32 v[70:71], v[74:75], v[72:73]
	v_fmac_f32_e32 v24, 0xba000000, v5
	v_fmac_f32_e32 v27, 0xba000000, v5
	v_fmac_f32_e32 v26, 0xba000000, v5
	v_fmac_f32_e32 v29, 0xba000000, v5
	v_fmac_f32_e32 v28, 0xba000000, v5
	v_fmac_f32_e32 v30, 0xba000000, v5
	v_fmac_f32_e32 v22, 0xba000000, v5
	v_mul_f32_e32 v5, v24, v24
	v_mul_f32_e32 v23, v32, v32
	v_pk_add_f32 v[68:69], v[68:69], v[68:69] op_sel:[0,1] op_sel_hi:[1,0]
	v_pk_add_f32 v[70:71], v[70:71], v[70:71] op_sel:[0,1] op_sel_hi:[1,0]
	v_mov_b32_e32 v69, v5
	v_mov_b32_e32 v71, v23
	v_mul_f32_e32 v48, v27, v27
	v_pk_add_f32 v[68:69], v[68:69], v[70:71]
	v_pk_fma_f32 v[70:71], v[26:27], v[26:27], v[48:49] op_sel_hi:[1,1,0]
	v_mul_f32_e32 v48, v29, v29
	v_mul_f32_e32 v25, v22, v22
	v_mul_f32_e32 v31, v30, v30
	v_pk_fma_f32 v[72:73], v[28:29], v[28:29], v[48:49] op_sel_hi:[1,1,0]
	v_mov_b32_e32 v71, v25
	v_mov_b32_e32 v73, v31
	v_pk_add_f32 v[70:71], v[70:71], v[72:73]
	v_mov_b32_e32 v39, v40
	v_pk_add_f32 v[68:69], v[68:69], v[70:71]
	v_mov_b32_e32 v35, v36
	v_add_f32_e32 v5, v68, v69
	global_load_dwordx4 v[68:71], v[6:7], off offset:16
	global_load_dwordx4 v[72:75], v[6:7], off
	global_load_dwordx4 v[76:79], v[8:9], off offset:16
	global_load_dwordx4 v[80:83], v[8:9], off
	ds_bpermute_b32 v23, v49, v5
	v_mov_b32_e32 v25, v32
	s_waitcnt lgkmcnt(0)
; __device__ __forceinline__ unsigned cvt_pk_bf16(float lo, float hi) { unsigned r; asm volatile("v_cvt_pk_bf16_f32 %0, %1, %2" : "=v"(r) : "v"(lo), "v"(hi)); return r; }
; __device__ __forceinline__ void ln_phase(const bf16_t* Y, const bf16_t* YP, const float* g, const float* b, float* of, bf16_t* ob, const int row_begin, const int row_stride, const int nwaves, const int nparts) {
;     ...
;         for (int o = 32; o >= 1; o >>= 1) q += __shfl_xor(q, o);
;         const float rstd = rsqrtf(q * (1.0f / 2048.0f) + LN_EPS);
; #pragma unroll
;         for (int i = 0; i < 4; ++i) { const int c = i * 512 + lane * 8;
;             const f32x4 g0 = *(const f32x4*)(g + c), g1 = *(const f32x4*)(g + c + 4), b0 = *(const f32x4*)(b + c), b1 = *(const f32x4*)(b + c + 4);
;             const f32x4 o0 = (v[2 * i] - mean) * rstd * g0 + b0, o1 = (v[2 * i + 1] - mean) * rstd * g1 + b1;
;             if (of) { *(f32x4*)(of + (size_t)row * DM + c) = o0; *(f32x4*)(of + (size_t)row * DM + c + 4) = o1; }
;             if (ob) { u32x4 w; w.x = cvt_pk_bf16(o0[0], o0[1]); w.y = cvt_pk_bf16(o0[2], o0[3]); w.z = cvt_pk_bf16(o1[0], o1[1]); w.w = cvt_pk_bf16(o1[2], o1[3]); *(u32x4*)(ob + (size_t)row * LDX + c) = w; } }
	v_add_f32_e32 v5, v5, v23
	ds_bpermute_b32 v23, v60, v5
	s_waitcnt lgkmcnt(0)
	v_add_f32_e32 v5, v5, v23
	ds_bpermute_b32 v23, v61, v5
	s_waitcnt lgkmcnt(0)
	v_add_f32_e32 v5, v5, v23
	ds_bpermute_b32 v23, v62, v5
	s_waitcnt lgkmcnt(0)
	v_add_f32_e32 v5, v5, v23
	ds_bpermute_b32 v23, v63, v5
	s_waitcnt lgkmcnt(0)
	v_add_f32_e32 v5, v5, v23
	ds_bpermute_b32 v23, v66, v5
	s_waitcnt lgkmcnt(0)
	v_add_f32_e32 v5, v5, v23
	v_fmamk_f32 v5, v5, 0x3a000000, v202
	v_cmp_gt_f32_e32 vcc, s10, v5
	v_mul_f32_e32 v23, 0x4b800000, v5
	s_nop 0
	v_cndmask_b32_e32 v5, v5, v23, vcc
	v_rsq_f32_e32 v5, v5
	s_nop 0
	v_mul_f32_e32 v23, 0x45800000, v5
	v_cndmask_b32_e32 v48, v5, v23, vcc
	v_pk_mul_f32 v[2:3], v[2:3], v[48:49] op_sel_hi:[1,0]
	v_pk_mul_f32 v[56:57], v[56:57], v[48:49] op_sel_hi:[1,0]
	v_pk_mul_f32 v[58:59], v[58:59], v[48:49] op_sel_hi:[1,0]
	v_pk_mul_f32 v[0:1], v[0:1], v[48:49] op_sel_hi:[1,0]
	v_pk_mul_f32 v[44:45], v[44:45], v[48:49] op_sel_hi:[1,0]
	v_pk_mul_f32 v[46:47], v[46:47], v[48:49] op_sel_hi:[1,0]
	v_pk_mul_f32 v[50:51], v[50:51], v[48:49] op_sel_hi:[1,0]
	v_pk_mul_f32 v[54:55], v[54:55], v[48:49] op_sel_hi:[1,0]
	v_pk_mul_f32 v[38:39], v[38:39], v[48:49] op_sel_hi:[1,0]
	v_pk_mul_f32 v[40:41], v[52:53], v[48:49] op_sel_hi:[1,0]
	v_pk_mul_f32 v[34:35], v[34:35], v[48:49] op_sel_hi:[1,0]
	v_mov_b32_e32 v23, v30
	v_pk_mul_f32 v[24:25], v[24:25], v[48:49] op_sel_hi:[1,0]
	v_pk_mul_f32 v[22:23], v[22:23], v[48:49] op_sel_hi:[1,0]
	v_pk_mul_f32 v[26:27], v[26:27], v[48:49] op_sel_hi:[1,0]
	v_pk_mul_f32 v[28:29], v[28:29], v[48:49] op_sel_hi:[1,0]
	s_waitcnt vmcnt(1)
	v_pk_fma_f32 v[56:57], v[70:71], v[56:57], v[78:79]
	s_waitcnt vmcnt(0)
	v_pk_fma_f32 v[2:3], v[72:73], v[2:3], v[80:81]
	v_pk_fma_f32 v[58:59], v[74:75], v[58:59], v[82:83]
	v_pk_fma_f32 v[68:69], v[68:69], v[0:1], v[76:77]
	v_cvt_pk_bf16_f32 v0, v2, v3
	v_cvt_pk_bf16_f32 v1, v58, v59
	s_nop 0
	v_cvt_pk_bf16_f32 v2, v68, v69
	v_cvt_pk_bf16_f32 v3, v56, v57
	v_lshl_add_u64 v[56:57], v[18:19], 0, v[64:65]
	v_add_co_u32_e32 v56, vcc, s2, v56
	v_lshl_add_u64 v[18:19], v[18:19], 0, s[8:9]
	s_nop 0
	v_addc_co_u32_e32 v57, vcc, 0, v57, vcc
	global_store_dwordx4 v[56:57], v[0:3], off
	s_nop 1
	global_load_dwordx4 v[0:3], v[6:7], off offset:2064
	s_nop 0
	global_load_dwordx4 v[68:71], v[6:7], off offset:2048
	global_load_dwordx4 v[72:75], v[8:9], off offset:2064
	global_load_dwordx4 v[76:79], v[8:9], off offset:2048
	v_cmp_lt_i32_e32 vcc, s38, v4
	s_or_b64 s[6:7], vcc, s[6:7]
	s_waitcnt vmcnt(1)
	v_pk_fma_f32 v[46:47], v[2:3], v[46:47], v[74:75]
	v_pk_fma_f32 v[2:3], v[0:1], v[44:45], v[72:73]
	s_waitcnt vmcnt(0)
	v_pk_fma_f32 v[54:55], v[70:71], v[54:55], v[78:79]
	v_pk_fma_f32 v[50:51], v[68:69], v[50:51], v[76:77]
	s_nop 0
	v_cvt_pk_bf16_f32 v0, v50, v51
	v_cvt_pk_bf16_f32 v1, v54, v55
	v_cvt_pk_bf16_f32 v2, v2, v3
	v_cvt_pk_bf16_f32 v3, v46, v47
	global_store_dwordx4 v[56:57], v[0:3], off offset:1024
	s_nop 1
	global_load_dwordx4 v[0:3], v[10:11], off offset:16
	s_nop 0
	global_load_dwordx4 v[44:47], v[10:11], off
	global_load_dwordx4 v[68:71], v[12:13], off offset:16
	global_load_dwordx4 v[72:75], v[12:13], off
	s_waitcnt vmcnt(1)
	v_pk_fma_f32 v[40:41], v[2:3], v[40:41], v[70:71]
	s_waitcnt vmcnt(0)
	v_pk_fma_f32 v[36:37], v[44:45], v[38:39], v[72:73]
	v_pk_mul_f32 v[38:39], v[42:43], v[48:49] op_sel_hi:[1,0]
	v_pk_fma_f32 v[34:35], v[46:47], v[34:35], v[74:75]
	v_pk_fma_f32 v[2:3], v[0:1], v[38:39], v[68:69]
	v_cvt_pk_bf16_f32 v0, v36, v37
	v_cvt_pk_bf16_f32 v1, v34, v35
	s_nop 0
	v_cvt_pk_bf16_f32 v2, v2, v3
	v_cvt_pk_bf16_f32 v3, v40, v41
	global_store_dwordx4 v[56:57], v[0:3], off offset:2048
	s_nop 1
	global_load_dwordx4 v[0:3], v[14:15], off offset:16
	s_nop 0
	global_load_dwordx4 v[34:37], v[14:15], off
	global_load_dwordx4 v[38:41], v[16:17], off offset:16
	global_load_dwordx4 v[42:45], v[16:17], off
	s_waitcnt vmcnt(1)
	v_pk_fma_f32 v[22:23], v[2:3], v[22:23], v[40:41]
	v_pk_fma_f32 v[2:3], v[0:1], v[24:25], v[38:39]
	s_waitcnt vmcnt(0)
	v_pk_fma_f32 v[28:29], v[36:37], v[28:29], v[44:45]
	v_pk_fma_f32 v[26:27], v[34:35], v[26:27], v[42:43]
	s_nop 0
	v_cvt_pk_bf16_f32 v0, v26, v27
	v_cvt_pk_bf16_f32 v1, v28, v29
	v_cvt_pk_bf16_f32 v2, v2, v3
	v_cvt_pk_bf16_f32 v3, v22, v23
	global_store_dwordx4 v[56:57], v[0:3], off offset:3072
	s_nop 1
	s_andn2_b64 exec, exec, s[6:7]
	s_cbranch_execnz .LBB0_131

; #define PG8_STAGE(bufoff, gbase, voff) do { _Pragma("unroll") for (int _i = 0; _i < 2; ++_i) \
;         __builtin_amdgcn_global_load_lds((const unsigned*)((const char*)(gbase) + (voff)[_i]), (LAS unsigned*)(lds + (bufoff) + ldsw + _i * 8192), 16, 0, 0); } while (0)
; #define PG8_LDA(dst, b, h) do { _Pragma("unroll") for (int m = 0; m < 4; ++m) _Pragma("unroll") for (int k = 0; k < 2; ++k) dst[m][k] = *(const LAS bf16x8*)(lds + PG8_SA(b, h) + aoff + m * 2048 + k * 1024); } while (0)
; #define PG8_LDB(dst, b, h) do { _Pragma("unroll") for (int n = 0; n < 2; ++n) _Pragma("unroll") for (int k = 0; k < 2; ++k) dst[n][k] = *(const LAS bf16x8*)(lds + PG8_SB(b, h) + boff + n * 2048 + k * 1024); } while (0)
; #define PG8_MMA(ai, bj, At, Bt) do { __builtin_amdgcn_s_setprio(1); _Pragma("unroll") for (int m = 0; m < 4; ++m) _Pragma("unroll") for (int n = 0; n < 2; ++n) _Pragma("unroll") for (int k = 0; k < 2; ++k) \
;         acc[ai][bj][m][n] = __builtin_amdgcn_mfma_f32_16x16x32_bf16(Bt[n][k], At[m][k], acc[ai][bj][m][n], 0, 0, 0); __builtin_amdgcn_s_setprio(0); } while (0)
; #define PG8_WAIT_L(n) asm volatile("s_waitcnt lgkmcnt(" #n ")" ::: "memory")
; #define PG8_BAR __builtin_amdgcn_s_barrier()
; #define PG8_SCHED __builtin_amdgcn_sched_barrier(0)
;     ...
;             const char* a1 = cA + (size_t)(t + 1) * kstep;
;             const char* a2 = last ? nA : cA + (size_t)(t + 2) * kstep; const char* b2 = last ? nB : cB + (size_t)(t + 2) * kstep;
;             const char* a3 = a2 + kstep; const char* b3 = b2 + kstep;
;             PG8_LDB(B0, 0, 0); PG8_SCHED; PG8_LDA(At, 0, 0); PG8_STAGE(PG8_SA(1, 1), a1 + hstep, voffA);
;             PG8_WAIT_L(8); PG8_BAR; PG8_WAIT_L(0); PG8_MMA(0, 0, At, B0); PG8_BAR; PG8_SCHED;
;             PG8_LDB(B1, 0, 1); PG8_STAGE(PG8_SB(0, 0), b2, voffB);
;             PG8_BAR; PG8_WAIT_L(0); PG8_MMA(0, 1, At, B1); PG8_BAR;
;             PG8_LDA(At, 0, 1); PG8_STAGE(PG8_SA(0, 0), a2, voffA);
;             PG8_BAR; PG8_WAIT_L(0); PG8_MMA(1, 0, At, B0); PG8_BAR; PG8_SCHED;
.LBB0_146:
	s_add_u32 s2, s8, 0xe515c080
	s_addc_u32 s3, s9, -1
	s_cmp_lg_u32 s27, 28
	s_cselect_b32 s10, s2, 0
	s_cselect_b32 s11, s3, 0
	s_add_u32 s2, s6, s10
	s_addc_u32 s3, s7, s11
	s_add_i32 s28, 0, 0x10000
	v_add_u32_e32 v156, s28, v142
	ds_read_b128 v[144:147], v156
	ds_read_b128 v[148:151], v156 offset:1024
	ds_read_b128 v[152:155], v156 offset:2048
	ds_read_b128 v[156:159], v156 offset:3072
	s_add_u32 s10, s4, s10
	s_addc_u32 s11, s5, s11
	v_lshl_add_u64 v[192:193], v[136:137], 0, s[8:9]
	s_add_i32 m0, s20, 0xc000
	ds_read_b128 v[160:163], v143
	ds_read_b128 v[164:167], v143 offset:1024
	ds_read_b128 v[168:171], v143 offset:2048
	ds_read_b128 v[172:175], v143 offset:3072
	ds_read_b128 v[176:179], v143 offset:4096
	ds_read_b128 v[180:183], v143 offset:5120
	ds_read_b128 v[184:187], v143 offset:6144
	ds_read_b128 v[188:191], v143 offset:7168
	global_load_lds_dwordx4 v[192:193], off
	v_lshl_add_u64 v[192:193], v[138:139], 0, s[8:9]
	s_add_i32 m0, s20, 0xe000
	s_nop 0
	global_load_lds_dwordx4 v[192:193], off
	s_waitcnt lgkmcnt(8)
	s_barrier
	s_waitcnt lgkmcnt(0)
	s_setprio 1
	s_waitcnt lgkmcnt(0)
	v_mfma_f32_16x16x32_bf16 v[126:129], v[144:147], v[160:163], v[126:129]
	v_mfma_f32_16x16x32_bf16 v[122:125], v[152:155], v[160:163], v[122:125]
	v_mfma_f32_16x16x32_bf16 v[110:113], v[144:147], v[168:171], v[110:113]
	v_mfma_f32_16x16x32_bf16 v[106:109], v[152:155], v[168:171], v[106:109]
	v_mfma_f32_16x16x32_bf16 v[94:97], v[144:147], v[176:179], v[94:97]
	v_mfma_f32_16x16x32_bf16 v[90:93], v[152:155], v[176:179], v[90:93]
	v_mfma_f32_16x16x32_bf16 v[78:81], v[144:147], v[184:187], v[78:81]
	v_mfma_f32_16x16x32_bf16 v[74:77], v[152:155], v[184:187], v[74:77]
	v_mfma_f32_16x16x32_bf16 v[126:129], v[148:151], v[164:167], v[126:129]
	v_mfma_f32_16x16x32_bf16 v[122:125], v[156:159], v[164:167], v[122:125]
	v_mfma_f32_16x16x32_bf16 v[110:113], v[148:151], v[172:175], v[110:113]
	v_mfma_f32_16x16x32_bf16 v[106:109], v[156:159], v[172:175], v[106:109]
	v_mfma_f32_16x16x32_bf16 v[94:97], v[148:151], v[180:183], v[94:97]
	v_mfma_f32_16x16x32_bf16 v[90:93], v[156:159], v[180:183], v[90:93]
	v_mfma_f32_16x16x32_bf16 v[78:81], v[148:151], v[188:191], v[78:81]
	v_mfma_f32_16x16x32_bf16 v[74:77], v[156:159], v[188:191], v[74:77]
	s_setprio 0
	s_barrier
	s_add_i32 s31, 0, 0x14000
	s_add_i32 s28, s28, s15
	v_add_u32_e32 v208, s31, v142
	v_lshl_add_u64 v[228:229], s[10:11], 0, v[64:65]
	s_mov_b32 m0, s28
	ds_read_b128 v[192:195], v208
	ds_read_b128 v[196:199], v208 offset:1024
	ds_read_b128 v[220:223], v208 offset:2048
	ds_read_b128 v[224:227], v208 offset:3072
	global_load_lds_dwordx4 v[228:229], off
	v_lshl_add_u64 v[230:231], s[10:11], 0, v[130:131]
	s_add_i32 m0, s28, 0x2000
	s_nop 0
	global_load_lds_dwordx4 v[230:231], off
	s_barrier
	s_waitcnt lgkmcnt(0)
	s_setprio 1
	s_waitcnt lgkmcnt(0)
	v_mfma_f32_16x16x32_bf16 v[118:121], v[192:195], v[160:163], v[118:121]
	v_mfma_f32_16x16x32_bf16 v[114:117], v[220:223], v[160:163], v[114:117]
	v_mfma_f32_16x16x32_bf16 v[102:105], v[192:195], v[168:171], v[102:105]
	v_mfma_f32_16x16x32_bf16 v[98:101], v[220:223], v[168:171], v[98:101]
	v_mfma_f32_16x16x32_bf16 v[86:89], v[192:195], v[176:179], v[86:89]
	v_mfma_f32_16x16x32_bf16 v[82:85], v[220:223], v[176:179], v[82:85]
	v_mfma_f32_16x16x32_bf16 v[70:73], v[192:195], v[184:187], v[70:73]
	v_mfma_f32_16x16x32_bf16 v[66:69], v[220:223], v[184:187], v[66:69]
	v_mfma_f32_16x16x32_bf16 v[118:121], v[196:199], v[164:167], v[118:121]
	v_mfma_f32_16x16x32_bf16 v[114:117], v[224:227], v[164:167], v[114:117]
	v_mfma_f32_16x16x32_bf16 v[102:105], v[196:199], v[172:175], v[102:105]
	v_mfma_f32_16x16x32_bf16 v[98:101], v[224:227], v[172:175], v[98:101]
	v_mfma_f32_16x16x32_bf16 v[86:89], v[196:199], v[180:183], v[86:89]
	v_mfma_f32_16x16x32_bf16 v[82:85], v[224:227], v[180:183], v[82:85]
	v_mfma_f32_16x16x32_bf16 v[70:73], v[196:199], v[188:191], v[70:73]
	v_mfma_f32_16x16x32_bf16 v[66:69], v[224:227], v[188:191], v[66:69]
	s_setprio 0
	s_mov_b32 m0, s20
	v_lshl_add_u64 v[232:233], s[2:3], 0, v[134:135]
	s_barrier
	ds_read_b128 v[160:163], v143 offset:16384
	ds_read_b128 v[164:167], v143 offset:17408
	ds_read_b128 v[168:171], v143 offset:18432
	ds_read_b128 v[172:175], v143 offset:19456
	ds_read_b128 v[176:179], v143 offset:20480
	ds_read_b128 v[180:183], v143 offset:21504
	ds_read_b128 v[184:187], v143 offset:22528
	ds_read_b128 v[188:191], v143 offset:23552
	global_load_lds_dwordx4 v[232:233], off
	v_lshl_add_u64 v[234:235], s[2:3], 0, v[132:133]
	s_mov_b32 m0, s21
	s_nop 0
	global_load_lds_dwordx4 v[234:235], off
	s_barrier
	s_waitcnt lgkmcnt(0)
	s_setprio 1
	s_waitcnt lgkmcnt(0)
	v_mfma_f32_16x16x32_bf16 v[60:63], v[144:147], v[160:163], v[60:63]
	v_mfma_f32_16x16x32_bf16 v[56:59], v[152:155], v[160:163], v[56:59]
	v_mfma_f32_16x16x32_bf16 v[44:47], v[144:147], v[168:171], v[44:47]
	v_mfma_f32_16x16x32_bf16 v[40:43], v[152:155], v[168:171], v[40:43]
	v_mfma_f32_16x16x32_bf16 v[28:31], v[144:147], v[176:179], v[28:31]
	v_mfma_f32_16x16x32_bf16 v[24:27], v[152:155], v[176:179], v[24:27]
	v_mfma_f32_16x16x32_bf16 v[12:15], v[144:147], v[184:187], v[12:15]
	v_mfma_f32_16x16x32_bf16 v[8:11], v[152:155], v[184:187], v[8:11]
	v_mfma_f32_16x16x32_bf16 v[60:63], v[148:151], v[164:167], v[60:63]
	v_mfma_f32_16x16x32_bf16 v[56:59], v[156:159], v[164:167], v[56:59]
	v_mfma_f32_16x16x32_bf16 v[44:47], v[148:151], v[172:175], v[44:47]
	v_mfma_f32_16x16x32_bf16 v[40:43], v[156:159], v[172:175], v[40:43]
	v_mfma_f32_16x16x32_bf16 v[28:31], v[148:151], v[180:183], v[28:31]
	v_mfma_f32_16x16x32_bf16 v[24:27], v[156:159], v[180:183], v[24:27]
	v_mfma_f32_16x16x32_bf16 v[12:15], v[148:151], v[188:191], v[12:15]
	v_mfma_f32_16x16x32_bf16 v[8:11], v[156:159], v[188:191], v[8:11]
	s_setprio 0
	s_barrier
; #define PG8_STAGE(bufoff, gbase, voff) do { _Pragma("unroll") for (int _i = 0; _i < 2; ++_i) \
;         __builtin_amdgcn_global_load_lds((const unsigned*)((const char*)(gbase) + (voff)[_i]), (LAS unsigned*)(lds + (bufoff) + ldsw + _i * 8192), 16, 0, 0); } while (0)
; #define PG8_LDA(dst, b, h) do { _Pragma("unroll") for (int m = 0; m < 4; ++m) _Pragma("unroll") for (int k = 0; k < 2; ++k) dst[m][k] = *(const LAS bf16x8*)(lds + PG8_SA(b, h) + aoff + m * 2048 + k * 1024); } while (0)
; #define PG8_LDB(dst, b, h) do { _Pragma("unroll") for (int n = 0; n < 2; ++n) _Pragma("unroll") for (int k = 0; k < 2; ++k) dst[n][k] = *(const LAS bf16x8*)(lds + PG8_SB(b, h) + boff + n * 2048 + k * 1024); } while (0)
; #define PG8_MMA(ai, bj, At, Bt) do { __builtin_amdgcn_s_setprio(1); _Pragma("unroll") for (int m = 0; m < 4; ++m) _Pragma("unroll") for (int n = 0; n < 2; ++n) _Pragma("unroll") for (int k = 0; k < 2; ++k) \
;         acc[ai][bj][m][n] = __builtin_amdgcn_mfma_f32_16x16x32_bf16(Bt[n][k], At[m][k], acc[ai][bj][m][n], 0, 0, 0); __builtin_amdgcn_s_setprio(0); } while (0)
; #define PG8_WAIT_V(n) asm volatile("s_waitcnt vmcnt(" #n ")" ::: "memory")
; #define PG8_WAIT_L(n) asm volatile("s_waitcnt lgkmcnt(" #n ")" ::: "memory")
; #define PG8_BAR __builtin_amdgcn_s_barrier()
; #define PG8_SCHED __builtin_amdgcn_sched_barrier(0)
;     ...
;             PG8_STAGE(PG8_SB(0, 1), b2 + hstep, voffB);
;             PG8_WAIT_V(6); PG8_BAR; PG8_MMA(1, 1, At, B1); PG8_BAR;
;             PG8_LDB(B0, 1, 0); PG8_SCHED; PG8_LDA(At, 1, 0); PG8_STAGE(PG8_SA(0, 1), a2 + hstep, voffA);
;             PG8_WAIT_L(8); PG8_BAR; PG8_WAIT_L(0); PG8_MMA(0, 0, At, B0); PG8_BAR; PG8_SCHED;
;             PG8_LDB(B1, 1, 1); PG8_STAGE(PG8_SB(1, 0), b3, voffB);
;             PG8_BAR; PG8_WAIT_L(0); PG8_MMA(0, 1, At, B1); PG8_BAR;
;             PG8_LDA(At, 1, 1); PG8_STAGE(PG8_SA(1, 0), a3, voffA);
;             PG8_BAR; PG8_WAIT_L(0); PG8_MMA(1, 0, At, B0); PG8_BAR; PG8_SCHED;
	s_add_u32 s28, s10, 0x84000
	s_addc_u32 s29, s11, 0
	s_add_i32 s31, s31, s15
	v_lshl_add_u64 v[144:145], s[28:29], 0, v[64:65]
	s_mov_b32 m0, s31
	s_nop 0
	global_load_lds_dwordx4 v[144:145], off
	v_lshl_add_u64 v[144:145], s[28:29], 0, v[130:131]
	s_add_i32 m0, s31, 0x2000
	s_nop 0
	global_load_lds_dwordx4 v[144:145], off
	s_waitcnt vmcnt(6)
	s_barrier
	s_setprio 1
	v_mfma_f32_16x16x32_bf16 v[52:55], v[192:195], v[160:163], v[52:55]
	v_mfma_f32_16x16x32_bf16 v[48:51], v[220:223], v[160:163], v[48:51]
	v_mfma_f32_16x16x32_bf16 v[36:39], v[192:195], v[168:171], v[36:39]
	v_mfma_f32_16x16x32_bf16 v[32:35], v[220:223], v[168:171], v[32:35]
	v_mfma_f32_16x16x32_bf16 v[20:23], v[192:195], v[176:179], v[20:23]
	v_mfma_f32_16x16x32_bf16 v[16:19], v[220:223], v[176:179], v[16:19]
	v_mfma_f32_16x16x32_bf16 v[4:7], v[192:195], v[184:187], v[4:7]
	v_mfma_f32_16x16x32_bf16 v[0:3], v[220:223], v[184:187], v[0:3]
	v_mfma_f32_16x16x32_bf16 v[52:55], v[196:199], v[164:167], v[52:55]
	v_mfma_f32_16x16x32_bf16 v[48:51], v[224:227], v[164:167], v[48:51]
	v_mfma_f32_16x16x32_bf16 v[36:39], v[196:199], v[172:175], v[36:39]
	v_mfma_f32_16x16x32_bf16 v[32:35], v[224:227], v[172:175], v[32:35]
	v_mfma_f32_16x16x32_bf16 v[20:23], v[196:199], v[180:183], v[20:23]
	v_mfma_f32_16x16x32_bf16 v[16:19], v[224:227], v[180:183], v[16:19]
	v_mfma_f32_16x16x32_bf16 v[4:7], v[196:199], v[188:191], v[4:7]
	v_mfma_f32_16x16x32_bf16 v[0:3], v[224:227], v[188:191], v[0:3]
	s_setprio 0
	s_add_i32 s28, 0, 0x18000
	v_add_u32_e32 v156, s28, v142
	s_barrier
	ds_read_b128 v[144:147], v156
	ds_read_b128 v[148:151], v156 offset:1024
	ds_read_b128 v[152:155], v156 offset:2048
	ds_read_b128 v[156:159], v156 offset:3072
	s_add_u32 s2, s2, 0x84000
	s_addc_u32 s3, s3, 0
	s_mov_b32 m0, s22
	v_lshl_add_u64 v[192:193], s[2:3], 0, v[134:135]
	ds_read_b128 v[160:163], v143 offset:32768
	ds_read_b128 v[164:167], v143 offset:33792
	ds_read_b128 v[168:171], v143 offset:34816
	ds_read_b128 v[172:175], v143 offset:35840
	ds_read_b128 v[176:179], v143 offset:36864
	ds_read_b128 v[180:183], v143 offset:37888
	ds_read_b128 v[184:187], v143 offset:38912
	ds_read_b128 v[188:191], v143 offset:39936
	global_load_lds_dwordx4 v[192:193], off
	v_lshl_add_u64 v[192:193], s[2:3], 0, v[132:133]
	s_mov_b32 m0, s23
	s_nop 0
	global_load_lds_dwordx4 v[192:193], off
	s_waitcnt lgkmcnt(8)
	s_barrier
	s_waitcnt lgkmcnt(0)
	s_setprio 1
	s_waitcnt lgkmcnt(0)
	v_mfma_f32_16x16x32_bf16 v[126:129], v[144:147], v[160:163], v[126:129]
	v_mfma_f32_16x16x32_bf16 v[122:125], v[152:155], v[160:163], v[122:125]
	v_mfma_f32_16x16x32_bf16 v[110:113], v[144:147], v[168:171], v[110:113]
	v_mfma_f32_16x16x32_bf16 v[106:109], v[152:155], v[168:171], v[106:109]
	v_mfma_f32_16x16x32_bf16 v[94:97], v[144:147], v[176:179], v[94:97]
	v_mfma_f32_16x16x32_bf16 v[90:93], v[152:155], v[176:179], v[90:93]
	v_mfma_f32_16x16x32_bf16 v[78:81], v[144:147], v[184:187], v[78:81]
	v_mfma_f32_16x16x32_bf16 v[74:77], v[152:155], v[184:187], v[74:77]
	v_mfma_f32_16x16x32_bf16 v[126:129], v[148:151], v[164:167], v[126:129]
	v_mfma_f32_16x16x32_bf16 v[122:125], v[156:159], v[164:167], v[122:125]
	v_mfma_f32_16x16x32_bf16 v[110:113], v[148:151], v[172:175], v[110:113]
	v_mfma_f32_16x16x32_bf16 v[106:109], v[156:159], v[172:175], v[106:109]
	v_mfma_f32_16x16x32_bf16 v[94:97], v[148:151], v[180:183], v[94:97]
	v_mfma_f32_16x16x32_bf16 v[90:93], v[156:159], v[180:183], v[90:93]
	v_mfma_f32_16x16x32_bf16 v[78:81], v[148:151], v[188:191], v[78:81]
	v_mfma_f32_16x16x32_bf16 v[74:77], v[156:159], v[188:191], v[74:77]
	s_setprio 0
	s_barrier
	s_add_i32 s29, 0, 0x1c000
	s_add_i32 s2, s28, s15
	v_add_u32_e32 v208, s29, v142
	v_lshl_add_u64 v[228:229], v[228:229], 0, s[16:17]
	s_mov_b32 m0, s2
	ds_read_b128 v[192:195], v208
	ds_read_b128 v[196:199], v208 offset:1024
	ds_read_b128 v[220:223], v208 offset:2048
	ds_read_b128 v[224:227], v208 offset:3072
	global_load_lds_dwordx4 v[228:229], off
	v_lshl_add_u64 v[228:229], v[230:231], 0, s[16:17]
	s_add_i32 m0, s2, 0x2000
	s_nop 0
	global_load_lds_dwordx4 v[228:229], off
	s_barrier
	s_waitcnt lgkmcnt(0)
	s_setprio 1
	s_waitcnt lgkmcnt(0)
	v_mfma_f32_16x16x32_bf16 v[118:121], v[192:195], v[160:163], v[118:121]
	v_mfma_f32_16x16x32_bf16 v[114:117], v[220:223], v[160:163], v[114:117]
	v_mfma_f32_16x16x32_bf16 v[102:105], v[192:195], v[168:171], v[102:105]
	v_mfma_f32_16x16x32_bf16 v[98:101], v[220:223], v[168:171], v[98:101]
	v_mfma_f32_16x16x32_bf16 v[86:89], v[192:195], v[176:179], v[86:89]
	v_mfma_f32_16x16x32_bf16 v[82:85], v[220:223], v[176:179], v[82:85]
	v_mfma_f32_16x16x32_bf16 v[70:73], v[192:195], v[184:187], v[70:73]
	v_mfma_f32_16x16x32_bf16 v[66:69], v[220:223], v[184:187], v[66:69]
	v_mfma_f32_16x16x32_bf16 v[118:121], v[196:199], v[164:167], v[118:121]
	v_mfma_f32_16x16x32_bf16 v[114:117], v[224:227], v[164:167], v[114:117]
	v_mfma_f32_16x16x32_bf16 v[102:105], v[196:199], v[172:175], v[102:105]
	v_mfma_f32_16x16x32_bf16 v[98:101], v[224:227], v[172:175], v[98:101]
	v_mfma_f32_16x16x32_bf16 v[86:89], v[196:199], v[180:183], v[86:89]
	v_mfma_f32_16x16x32_bf16 v[82:85], v[224:227], v[180:183], v[82:85]
	v_mfma_f32_16x16x32_bf16 v[70:73], v[196:199], v[188:191], v[70:73]
	v_mfma_f32_16x16x32_bf16 v[66:69], v[224:227], v[188:191], v[66:69]
	s_setprio 0
	s_mov_b32 m0, s25
	v_lshl_add_u64 v[228:229], v[232:233], 0, s[16:17]
	s_barrier
	ds_read_b128 v[160:163], v143 offset:49152
	ds_read_b128 v[164:167], v143 offset:50176
	ds_read_b128 v[168:171], v143 offset:51200
	ds_read_b128 v[172:175], v143 offset:52224
	ds_read_b128 v[176:179], v143 offset:53248
	ds_read_b128 v[180:183], v143 offset:54272
	ds_read_b128 v[184:187], v143 offset:55296
	ds_read_b128 v[188:191], v143 offset:56320
	global_load_lds_dwordx4 v[228:229], off
	v_lshl_add_u64 v[228:229], v[234:235], 0, s[16:17]
	s_mov_b32 m0, s26
	s_nop 0
	global_load_lds_dwordx4 v[228:229], off
	s_barrier
; __device__ __forceinline__ unsigned cvt_pk_bf16(float lo, float hi) { unsigned r; asm volatile("v_cvt_pk_bf16_f32 %0, %1, %2" : "=v"(r) : "v"(lo), "v"(hi)); return r; }
; #define PG8_STAGE(bufoff, gbase, voff) do { _Pragma("unroll") for (int _i = 0; _i < 2; ++_i) \
;         __builtin_amdgcn_global_load_lds((const unsigned*)((const char*)(gbase) + (voff)[_i]), (LAS unsigned*)(lds + (bufoff) + ldsw + _i * 8192), 16, 0, 0); } while (0)
; #define PG8_LDA(dst, b, h) do { _Pragma("unroll") for (int m = 0; m < 4; ++m) _Pragma("unroll") for (int k = 0; k < 2; ++k) dst[m][k] = *(const LAS bf16x8*)(lds + PG8_SA(b, h) + aoff + m * 2048 + k * 1024); } while (0)
; #define PG8_LDB(dst, b, h) do { _Pragma("unroll") for (int n = 0; n < 2; ++n) _Pragma("unroll") for (int k = 0; k < 2; ++k) dst[n][k] = *(const LAS bf16x8*)(lds + PG8_SB(b, h) + boff + n * 2048 + k * 1024); } while (0)
; #define PG8_BAR __builtin_amdgcn_s_barrier()
;     __device__ __forceinline__ void operator()(const f32x4 (&acc)[2][2][4][2], const Unit& u, int wr, int wc, int fr, int fq) const {
;     ...
;             for (int m = 0; m < 4; ++m) { bf16_t* rowp = O + (size_t)(row0 + ai * HALF + m * 16) * LDF + col0;
; #pragma unroll
;                 for (int bj = 0; bj < 2; ++bj) { f32x4 v0 = acc[ai][bj][m][0], v1 = acc[ai][bj][m][1];
; #pragma unroll
;                     for (int j = 0; j < 4; ++j) { const float a = fmaxf(v0[j], 0.f), b = fmaxf(v1[j], 0.f); v0[j] = a * a; v1[j] = b * b; }
;                     u32x4 w; w.x = cvt_pk_bf16(v0[0], v0[1]); w.y = cvt_pk_bf16(v0[2], v0[3]); w.z = cvt_pk_bf16(v1[0], v1[1]); w.w = cvt_pk_bf16(v1[2], v1[3]);
;                     *(u32x4*)(rowp + bj * HALF) = w; } }
;     ...
;             PG8_WAIT_V(6); PG8_BAR; PG8_MMA(1, 1, At, B1); PG8_BAR;
;             PG8_LDB(B0, 1, 0); PG8_SCHED; PG8_LDA(At, 1, 0); PG8_STAGE(PG8_SA(0, 1), a2 + hstep, voffA);
;             PG8_WAIT_L(8); PG8_BAR; PG8_WAIT_L(0); PG8_MMA(0, 0, At, B0); PG8_BAR; PG8_SCHED;
;             PG8_LDB(B1, 1, 1); PG8_STAGE(PG8_SB(1, 0), b3, voffB);
;             PG8_BAR; PG8_WAIT_L(0); PG8_MMA(0, 1, At, B1); PG8_BAR;
;             PG8_LDA(At, 1, 1); PG8_STAGE(PG8_SA(1, 0), a3, voffA);
;             PG8_BAR; PG8_WAIT_L(0); PG8_MMA(1, 0, At, B0); PG8_BAR; PG8_SCHED;
;             PG8_STAGE(PG8_SB(1, 1), b3 + hstep, voffB);
;             PG8_WAIT_V(6); PG8_BAR; PG8_MMA(1, 1, At, B1); PG8_BAR;
	s_waitcnt lgkmcnt(0)
	s_setprio 1
	s_waitcnt lgkmcnt(0)
	v_mfma_f32_16x16x32_bf16 v[60:63], v[144:147], v[160:163], v[60:63]
	v_mfma_f32_16x16x32_bf16 v[56:59], v[152:155], v[160:163], v[56:59]
	v_mfma_f32_16x16x32_bf16 v[44:47], v[144:147], v[168:171], v[44:47]
	v_mfma_f32_16x16x32_bf16 v[40:43], v[152:155], v[168:171], v[40:43]
	v_mfma_f32_16x16x32_bf16 v[28:31], v[144:147], v[176:179], v[28:31]
	v_mfma_f32_16x16x32_bf16 v[24:27], v[152:155], v[176:179], v[24:27]
	v_mfma_f32_16x16x32_bf16 v[12:15], v[144:147], v[184:187], v[12:15]
	v_mfma_f32_16x16x32_bf16 v[8:11], v[152:155], v[184:187], v[8:11]
	v_mfma_f32_16x16x32_bf16 v[60:63], v[148:151], v[164:167], v[60:63]
	v_mfma_f32_16x16x32_bf16 v[56:59], v[156:159], v[164:167], v[56:59]
	v_mfma_f32_16x16x32_bf16 v[44:47], v[148:151], v[172:175], v[44:47]
	v_mfma_f32_16x16x32_bf16 v[40:43], v[156:159], v[172:175], v[40:43]
	v_mfma_f32_16x16x32_bf16 v[28:31], v[148:151], v[180:183], v[28:31]
	v_mfma_f32_16x16x32_bf16 v[24:27], v[156:159], v[180:183], v[24:27]
	v_mfma_f32_16x16x32_bf16 v[12:15], v[148:151], v[188:191], v[12:15]
	v_mfma_f32_16x16x32_bf16 v[8:11], v[156:159], v[188:191], v[8:11]
	s_setprio 0
	s_barrier
	s_add_u32 s2, s10, 0x84080
	s_addc_u32 s3, s11, 0
	s_add_i32 s10, s29, s15
	v_lshl_add_u64 v[144:145], s[2:3], 0, v[64:65]
	s_mov_b32 m0, s10
	s_nop 0
	global_load_lds_dwordx4 v[144:145], off
	v_lshl_add_u64 v[144:145], s[2:3], 0, v[130:131]
	s_add_i32 m0, s10, 0x2000
	s_nop 0
	global_load_lds_dwordx4 v[144:145], off
	s_waitcnt vmcnt(6)
	s_barrier
	s_setprio 1
	v_mfma_f32_16x16x32_bf16 v[52:55], v[192:195], v[160:163], v[52:55]
	v_mfma_f32_16x16x32_bf16 v[48:51], v[220:223], v[160:163], v[48:51]
	v_mfma_f32_16x16x32_bf16 v[36:39], v[192:195], v[168:171], v[36:39]
	v_mfma_f32_16x16x32_bf16 v[32:35], v[220:223], v[168:171], v[32:35]
	v_mfma_f32_16x16x32_bf16 v[20:23], v[192:195], v[176:179], v[20:23]
	v_mfma_f32_16x16x32_bf16 v[16:19], v[220:223], v[176:179], v[16:19]
	v_mfma_f32_16x16x32_bf16 v[4:7], v[192:195], v[184:187], v[4:7]
	v_mfma_f32_16x16x32_bf16 v[0:3], v[220:223], v[184:187], v[0:3]
	v_mfma_f32_16x16x32_bf16 v[52:55], v[196:199], v[164:167], v[52:55]
	v_mfma_f32_16x16x32_bf16 v[48:51], v[224:227], v[164:167], v[48:51]
	v_mfma_f32_16x16x32_bf16 v[36:39], v[196:199], v[172:175], v[36:39]
	v_mfma_f32_16x16x32_bf16 v[32:35], v[224:227], v[172:175], v[32:35]
	v_mfma_f32_16x16x32_bf16 v[20:23], v[196:199], v[180:183], v[20:23]
	v_mfma_f32_16x16x32_bf16 v[16:19], v[224:227], v[180:183], v[16:19]
	v_mfma_f32_16x16x32_bf16 v[4:7], v[196:199], v[188:191], v[4:7]
	v_mfma_f32_16x16x32_bf16 v[0:3], v[224:227], v[188:191], v[0:3]
	s_setprio 0
	s_add_i32 s27, s27, 2
	s_add_u32 s8, s8, 0x100
	s_addc_u32 s9, s9, 0
	s_cmp_gt_u32 s27, 29
	s_barrier
	s_cbranch_scc0 .LBB0_146
	s_lshl_b32 s2, s19, 8
	v_max_f32_e32 v122, 0, v122
	s_or_b32 s2, s24, s2
	v_mul_f32_e32 v135, v122, v122
	v_max_f32_e32 v122, v127, v127
	v_max_f32_e32 v123, 0, v123
	v_max_f32_e32 v124, 0, v124
	v_lshl_add_u32 v134, s18, 8, v141
	v_or_b32_e32 v64, s2, v140
	v_mov_b64_e32 v[130:131], s[80:81]
	s_movk_i32 s4, 0x4080
	v_max_f32_e32 v122, 0, v122
	v_mul_f32_e32 v127, v123, v123
	v_max_f32_e32 v123, v128, v128
	v_mul_f32_e32 v128, v124, v124
	v_max_f32_e32 v124, v129, v129
	v_mad_i64_i32 v[132:133], s[2:3], v134, s4, v[130:131]
	v_lshlrev_b32_e32 v64, 1, v64
	v_max_f32_e32 v126, 0, v126
	v_mul_f32_e32 v122, v122, v122
	v_max_f32_e32 v123, 0, v123
	v_max_f32_e32 v124, 0, v124
	v_max_f32_e32 v125, 0, v125
	v_lshl_add_u64 v[132:133], v[132:133], 0, v[64:65]
	v_mul_f32_e32 v126, v126, v126
	v_mul_f32_e32 v123, v123, v123
	v_mul_f32_e32 v124, v124, v124
	v_mul_f32_e32 v125, v125, v125
	v_cvt_pk_bf16_f32 v122, v126, v122
	v_max_f32_e32 v114, 0, v114
	v_max_f32_e32 v115, 0, v115
	v_max_f32_e32 v116, 0, v116
	v_cvt_pk_bf16_f32 v123, v123, v124
	v_cvt_pk_bf16_f32 v124, v135, v127
	v_cvt_pk_bf16_f32 v125, v128, v125
	global_store_dwordx4 v[132:133], v[122:125], off
	s_nop 1
	v_mul_f32_e32 v122, v114, v114
	v_max_f32_e32 v114, v119, v119
	v_mul_f32_e32 v119, v115, v115
	v_max_f32_e32 v115, v120, v120
	v_mul_f32_e32 v120, v116, v116
	v_max_f32_e32 v116, v121, v121
	v_max_f32_e32 v114, 0, v114
	v_max_f32_e32 v115, 0, v115
	v_max_f32_e32 v116, 0, v116
	v_max_f32_e32 v118, 0, v118
	v_mul_f32_e32 v114, v114, v114
	v_mul_f32_e32 v115, v115, v115
	v_max_f32_e32 v117, 0, v117
	v_mul_f32_e32 v116, v116, v116
	v_mul_f32_e32 v118, v118, v118
	v_mul_f32_e32 v117, v117, v117
	v_cvt_pk_bf16_f32 v114, v118, v114
	v_cvt_pk_bf16_f32 v115, v115, v116
	v_cvt_pk_bf16_f32 v116, v122, v119
	v_max_f32_e32 v106, 0, v106
	v_cvt_pk_bf16_f32 v117, v120, v117
	global_store_dwordx4 v[132:133], v[114:117], off offset:256
	s_nop 1
	v_max_f32_e32 v107, 0, v107
	v_max_f32_e32 v108, 0, v108
	v_mul_f32_e32 v116, v106, v106
	v_max_f32_e32 v106, v111, v111
	v_or_b32_e32 v114, 16, v134
	v_max_f32_e32 v106, 0, v106
	v_mul_f32_e32 v111, v107, v107
	v_max_f32_e32 v107, v112, v112
	v_mul_f32_e32 v112, v108, v108
	v_max_f32_e32 v108, v113, v113
	v_mad_i64_i32 v[114:115], s[2:3], v114, s4, v[130:131]
	v_max_f32_e32 v110, 0, v110
	v_mul_f32_e32 v106, v106, v106
	v_max_f32_e32 v107, 0, v107
	v_max_f32_e32 v108, 0, v108
	v_max_f32_e32 v109, 0, v109
	v_lshl_add_u64 v[114:115], v[114:115], 0, v[64:65]
	v_mul_f32_e32 v110, v110, v110
	v_mul_f32_e32 v107, v107, v107
	v_mul_f32_e32 v108, v108, v108
	v_mul_f32_e32 v109, v109, v109
	v_cvt_pk_bf16_f32 v106, v110, v106
	v_max_f32_e32 v98, 0, v98
	v_max_f32_e32 v99, 0, v99
	v_max_f32_e32 v100, 0, v100
	v_cvt_pk_bf16_f32 v107, v107, v108
	v_cvt_pk_bf16_f32 v108, v116, v111
	v_cvt_pk_bf16_f32 v109, v112, v109
	global_store_dwordx4 v[114:115], v[106:109], off
; __device__ __forceinline__ unsigned cvt_pk_bf16(float lo, float hi) { unsigned r; asm volatile("v_cvt_pk_bf16_f32 %0, %1, %2" : "=v"(r) : "v"(lo), "v"(hi)); return r; }
;     __device__ __forceinline__ void operator()(const f32x4 (&acc)[2][2][4][2], const Unit& u, int wr, int wc, int fr, int fq) const {
;     ...
;             for (int m = 0; m < 4; ++m) { bf16_t* rowp = O + (size_t)(row0 + ai * HALF + m * 16) * LDF + col0;
; #pragma unroll
;                 for (int bj = 0; bj < 2; ++bj) { f32x4 v0 = acc[ai][bj][m][0], v1 = acc[ai][bj][m][1];
; #pragma unroll
;                     for (int j = 0; j < 4; ++j) { const float a = fmaxf(v0[j], 0.f), b = fmaxf(v1[j], 0.f); v0[j] = a * a; v1[j] = b * b; }
;                     u32x4 w; w.x = cvt_pk_bf16(v0[0], v0[1]); w.y = cvt_pk_bf16(v0[2], v0[3]); w.z = cvt_pk_bf16(v1[0], v1[1]); w.w = cvt_pk_bf16(v1[2], v1[3]);
;                     *(u32x4*)(rowp + bj * HALF) = w; } }
	s_nop 1
	v_mul_f32_e32 v106, v98, v98
	v_max_f32_e32 v98, v103, v103
	v_mul_f32_e32 v103, v99, v99
	v_max_f32_e32 v99, v104, v104
	v_mul_f32_e32 v104, v100, v100
	v_max_f32_e32 v100, v105, v105
	v_max_f32_e32 v98, 0, v98
	v_max_f32_e32 v99, 0, v99
	v_max_f32_e32 v100, 0, v100
	v_max_f32_e32 v102, 0, v102
	v_mul_f32_e32 v98, v98, v98
	v_mul_f32_e32 v99, v99, v99
	v_max_f32_e32 v101, 0, v101
	v_mul_f32_e32 v100, v100, v100
	v_mul_f32_e32 v102, v102, v102
	v_mul_f32_e32 v101, v101, v101
	v_cvt_pk_bf16_f32 v98, v102, v98
	v_cvt_pk_bf16_f32 v99, v99, v100
	v_cvt_pk_bf16_f32 v100, v106, v103
	v_max_f32_e32 v90, 0, v90
	v_cvt_pk_bf16_f32 v101, v104, v101
	global_store_dwordx4 v[114:115], v[98:101], off offset:256
	s_nop 1
	v_max_f32_e32 v91, 0, v91
	v_max_f32_e32 v92, 0, v92
	v_mul_f32_e32 v100, v90, v90
	v_max_f32_e32 v90, v95, v95
	v_or_b32_e32 v98, 32, v134
	v_max_f32_e32 v90, 0, v90
	v_mul_f32_e32 v95, v91, v91
	v_max_f32_e32 v91, v96, v96
	v_mul_f32_e32 v96, v92, v92
	v_max_f32_e32 v92, v97, v97
	v_mad_i64_i32 v[98:99], s[2:3], v98, s4, v[130:131]
	v_max_f32_e32 v94, 0, v94
	v_mul_f32_e32 v90, v90, v90
	v_max_f32_e32 v91, 0, v91
	v_max_f32_e32 v92, 0, v92
	v_max_f32_e32 v93, 0, v93
	v_lshl_add_u64 v[98:99], v[98:99], 0, v[64:65]
	v_mul_f32_e32 v94, v94, v94
	v_mul_f32_e32 v91, v91, v91
	v_mul_f32_e32 v92, v92, v92
	v_mul_f32_e32 v93, v93, v93
	v_cvt_pk_bf16_f32 v90, v94, v90
	v_max_f32_e32 v82, 0, v82
	v_max_f32_e32 v83, 0, v83
	v_max_f32_e32 v84, 0, v84
	v_cvt_pk_bf16_f32 v91, v91, v92
	v_cvt_pk_bf16_f32 v92, v100, v95
	v_cvt_pk_bf16_f32 v93, v96, v93
	global_store_dwordx4 v[98:99], v[90:93], off
	s_nop 1
	v_mul_f32_e32 v90, v82, v82
	v_max_f32_e32 v82, v87, v87
	v_mul_f32_e32 v87, v83, v83
	v_max_f32_e32 v83, v88, v88
	v_mul_f32_e32 v88, v84, v84
	v_max_f32_e32 v84, v89, v89
	v_max_f32_e32 v82, 0, v82
	v_max_f32_e32 v83, 0, v83
	v_max_f32_e32 v84, 0, v84
	v_max_f32_e32 v86, 0, v86
	v_mul_f32_e32 v82, v82, v82
	v_mul_f32_e32 v83, v83, v83
	v_max_f32_e32 v85, 0, v85
	v_mul_f32_e32 v84, v84, v84
	v_mul_f32_e32 v86, v86, v86
	v_mul_f32_e32 v85, v85, v85
	v_cvt_pk_bf16_f32 v82, v86, v82
	v_cvt_pk_bf16_f32 v83, v83, v84
	v_cvt_pk_bf16_f32 v84, v90, v87
	v_max_f32_e32 v74, 0, v74
	v_cvt_pk_bf16_f32 v85, v88, v85
	global_store_dwordx4 v[98:99], v[82:85], off offset:256
	s_nop 1
	v_max_f32_e32 v75, 0, v75
	v_max_f32_e32 v76, 0, v76
	v_mul_f32_e32 v84, v74, v74
	v_max_f32_e32 v74, v79, v79
	v_or_b32_e32 v82, 48, v134
	v_max_f32_e32 v74, 0, v74
	v_mul_f32_e32 v79, v75, v75
	v_max_f32_e32 v75, v80, v80
	v_mul_f32_e32 v80, v76, v76
	v_max_f32_e32 v76, v81, v81
	v_mad_i64_i32 v[82:83], s[2:3], v82, s4, v[130:131]
	v_max_f32_e32 v78, 0, v78
	v_mul_f32_e32 v74, v74, v74
	v_max_f32_e32 v75, 0, v75
	v_max_f32_e32 v76, 0, v76
	v_max_f32_e32 v77, 0, v77
	v_lshl_add_u64 v[82:83], v[82:83], 0, v[64:65]
	v_mul_f32_e32 v78, v78, v78
	v_mul_f32_e32 v75, v75, v75
	v_mul_f32_e32 v76, v76, v76
	v_mul_f32_e32 v77, v77, v77
	v_cvt_pk_bf16_f32 v74, v78, v74
	v_max_f32_e32 v66, 0, v66
	v_max_f32_e32 v67, 0, v67
	v_max_f32_e32 v68, 0, v68
	v_cvt_pk_bf16_f32 v75, v75, v76
	v_cvt_pk_bf16_f32 v76, v84, v79
	v_cvt_pk_bf16_f32 v77, v80, v77
	global_store_dwordx4 v[82:83], v[74:77], off
	s_nop 1
	v_mul_f32_e32 v74, v66, v66
	v_max_f32_e32 v66, v71, v71
	v_mul_f32_e32 v71, v67, v67
	v_max_f32_e32 v67, v72, v72
	v_mul_f32_e32 v72, v68, v68
	v_max_f32_e32 v68, v73, v73
	v_max_f32_e32 v66, 0, v66
	v_max_f32_e32 v67, 0, v67
	v_max_f32_e32 v68, 0, v68
	v_max_f32_e32 v70, 0, v70
	v_mul_f32_e32 v66, v66, v66
	v_mul_f32_e32 v67, v67, v67
	v_max_f32_e32 v69, 0, v69
	v_mul_f32_e32 v68, v68, v68
	v_mul_f32_e32 v70, v70, v70
	v_mul_f32_e32 v69, v69, v69
	v_cvt_pk_bf16_f32 v66, v70, v66
	v_cvt_pk_bf16_f32 v67, v67, v68
	v_cvt_pk_bf16_f32 v68, v74, v71
	v_max_f32_e32 v56, 0, v56
	v_cvt_pk_bf16_f32 v69, v72, v69
	global_store_dwordx4 v[82:83], v[66:69], off offset:256
	s_nop 1
	v_max_f32_e32 v57, 0, v57
	v_max_f32_e32 v58, 0, v58
	v_mul_f32_e32 v68, v56, v56
	v_max_f32_e32 v56, v61, v61
	v_add_u32_e32 v66, 0x80, v134
	v_max_f32_e32 v56, 0, v56
	v_mul_f32_e32 v61, v57, v57
	v_max_f32_e32 v57, v62, v62
	v_mul_f32_e32 v62, v58, v58
	v_max_f32_e32 v58, v63, v63
	v_mad_i64_i32 v[66:67], s[2:3], v66, s4, v[130:131]
	v_max_f32_e32 v60, 0, v60
	v_mul_f32_e32 v56, v56, v56
	v_max_f32_e32 v57, 0, v57
	v_max_f32_e32 v58, 0, v58
	v_max_f32_e32 v59, 0, v59
	v_lshl_add_u64 v[66:67], v[66:67], 0, v[64:65]
	v_mul_f32_e32 v60, v60, v60
	v_mul_f32_e32 v57, v57, v57
	v_mul_f32_e32 v58, v58, v58
	v_mul_f32_e32 v59, v59, v59
	v_cvt_pk_bf16_f32 v56, v60, v56
	v_max_f32_e32 v48, 0, v48
	v_max_f32_e32 v49, 0, v49
	v_max_f32_e32 v50, 0, v50
	v_cvt_pk_bf16_f32 v57, v57, v58
	v_cvt_pk_bf16_f32 v58, v68, v61
	v_cvt_pk_bf16_f32 v59, v62, v59
	global_store_dwordx4 v[66:67], v[56:59], off
	s_nop 1
	v_mul_f32_e32 v56, v48, v48
	v_max_f32_e32 v48, v53, v53
	v_mul_f32_e32 v53, v49, v49
	v_max_f32_e32 v49, v54, v54
	v_mul_f32_e32 v54, v50, v50
	v_max_f32_e32 v50, v55, v55
	v_max_f32_e32 v48, 0, v48
	v_max_f32_e32 v49, 0, v49
	v_max_f32_e32 v50, 0, v50
	v_max_f32_e32 v52, 0, v52
	v_mul_f32_e32 v48, v48, v48
; __device__ __forceinline__ unsigned cvt_pk_bf16(float lo, float hi) { unsigned r; asm volatile("v_cvt_pk_bf16_f32 %0, %1, %2" : "=v"(r) : "v"(lo), "v"(hi)); return r; }
; #define PG8_WAIT_V(n) asm volatile("s_waitcnt vmcnt(" #n ")" ::: "memory")
; #define PG8_BAR __builtin_amdgcn_s_barrier()
;     __device__ __forceinline__ void operator()(const f32x4 (&acc)[2][2][4][2], const Unit& u, int wr, int wc, int fr, int fq) const {
;     ...
;             for (int m = 0; m < 4; ++m) { bf16_t* rowp = O + (size_t)(row0 + ai * HALF + m * 16) * LDF + col0;
; #pragma unroll
;                 for (int bj = 0; bj < 2; ++bj) { f32x4 v0 = acc[ai][bj][m][0], v1 = acc[ai][bj][m][1];
; #pragma unroll
;                     for (int j = 0; j < 4; ++j) { const float a = fmaxf(v0[j], 0.f), b = fmaxf(v1[j], 0.f); v0[j] = a * a; v1[j] = b * b; }
;                     u32x4 w; w.x = cvt_pk_bf16(v0[0], v0[1]); w.y = cvt_pk_bf16(v0[2], v0[3]); w.z = cvt_pk_bf16(v1[0], v1[1]); w.w = cvt_pk_bf16(v1[2], v1[3]);
;                     *(u32x4*)(rowp + bj * HALF) = w; } }
;     ...
;     PG8_WAIT_V(0);
;     if (wr == 0) PG8_BAR;
	v_mul_f32_e32 v49, v49, v49
	v_max_f32_e32 v51, 0, v51
	v_mul_f32_e32 v50, v50, v50
	v_mul_f32_e32 v52, v52, v52
	v_mul_f32_e32 v51, v51, v51
	v_cvt_pk_bf16_f32 v48, v52, v48
	v_cvt_pk_bf16_f32 v49, v49, v50
	v_cvt_pk_bf16_f32 v50, v56, v53
	v_max_f32_e32 v40, 0, v40
	v_cvt_pk_bf16_f32 v51, v54, v51
	global_store_dwordx4 v[66:67], v[48:51], off offset:256
	s_nop 1
	v_max_f32_e32 v41, 0, v41
	v_max_f32_e32 v42, 0, v42
	v_mul_f32_e32 v50, v40, v40
	v_max_f32_e32 v40, v45, v45
	v_add_u32_e32 v48, 0x90, v134
	v_max_f32_e32 v40, 0, v40
	v_mul_f32_e32 v45, v41, v41
	v_max_f32_e32 v41, v46, v46
	v_mul_f32_e32 v46, v42, v42
	v_max_f32_e32 v42, v47, v47
	v_mad_i64_i32 v[48:49], s[2:3], v48, s4, v[130:131]
	v_max_f32_e32 v44, 0, v44
	v_mul_f32_e32 v40, v40, v40
	v_max_f32_e32 v41, 0, v41
	v_max_f32_e32 v42, 0, v42
	v_max_f32_e32 v43, 0, v43
	v_lshl_add_u64 v[48:49], v[48:49], 0, v[64:65]
	v_mul_f32_e32 v44, v44, v44
	v_mul_f32_e32 v41, v41, v41
	v_mul_f32_e32 v42, v42, v42
	v_mul_f32_e32 v43, v43, v43
	v_cvt_pk_bf16_f32 v40, v44, v40
	v_max_f32_e32 v32, 0, v32
	v_max_f32_e32 v33, 0, v33
	v_max_f32_e32 v34, 0, v34
	v_cvt_pk_bf16_f32 v41, v41, v42
	v_cvt_pk_bf16_f32 v42, v50, v45
	v_cvt_pk_bf16_f32 v43, v46, v43
	global_store_dwordx4 v[48:49], v[40:43], off
	s_nop 1
	v_mul_f32_e32 v40, v32, v32
	v_max_f32_e32 v32, v37, v37
	v_mul_f32_e32 v37, v33, v33
	v_max_f32_e32 v33, v38, v38
	v_mul_f32_e32 v38, v34, v34
	v_max_f32_e32 v34, v39, v39
	v_max_f32_e32 v32, 0, v32
	v_max_f32_e32 v33, 0, v33
	v_max_f32_e32 v34, 0, v34
	v_max_f32_e32 v36, 0, v36
	v_mul_f32_e32 v32, v32, v32
	v_mul_f32_e32 v33, v33, v33
	v_max_f32_e32 v35, 0, v35
	v_mul_f32_e32 v34, v34, v34
	v_mul_f32_e32 v36, v36, v36
	v_mul_f32_e32 v35, v35, v35
	v_cvt_pk_bf16_f32 v32, v36, v32
	v_cvt_pk_bf16_f32 v33, v33, v34
	v_cvt_pk_bf16_f32 v34, v40, v37
	v_max_f32_e32 v24, 0, v24
	v_cvt_pk_bf16_f32 v35, v38, v35
	global_store_dwordx4 v[48:49], v[32:35], off offset:256
	s_nop 1
	v_max_f32_e32 v25, 0, v25
	v_max_f32_e32 v26, 0, v26
	v_mul_f32_e32 v34, v24, v24
	v_max_f32_e32 v24, v29, v29
	v_add_u32_e32 v32, 0xa0, v134
	v_max_f32_e32 v24, 0, v24
	v_mul_f32_e32 v29, v25, v25
	v_max_f32_e32 v25, v30, v30
	v_mul_f32_e32 v30, v26, v26
	v_max_f32_e32 v26, v31, v31
	v_mad_i64_i32 v[32:33], s[2:3], v32, s4, v[130:131]
	v_max_f32_e32 v28, 0, v28
	v_mul_f32_e32 v24, v24, v24
	v_max_f32_e32 v25, 0, v25
	v_max_f32_e32 v26, 0, v26
	v_max_f32_e32 v27, 0, v27
	v_lshl_add_u64 v[32:33], v[32:33], 0, v[64:65]
	v_mul_f32_e32 v28, v28, v28
	v_mul_f32_e32 v25, v25, v25
	v_mul_f32_e32 v26, v26, v26
	v_mul_f32_e32 v27, v27, v27
	v_cvt_pk_bf16_f32 v24, v28, v24
	v_max_f32_e32 v16, 0, v16
	v_max_f32_e32 v17, 0, v17
	v_max_f32_e32 v18, 0, v18
	v_cvt_pk_bf16_f32 v25, v25, v26
	v_cvt_pk_bf16_f32 v26, v34, v29
	v_cvt_pk_bf16_f32 v27, v30, v27
	global_store_dwordx4 v[32:33], v[24:27], off
	s_nop 1
	v_mul_f32_e32 v24, v16, v16
	v_max_f32_e32 v16, v21, v21
	v_mul_f32_e32 v21, v17, v17
	v_max_f32_e32 v17, v22, v22
	v_mul_f32_e32 v22, v18, v18
	v_max_f32_e32 v18, v23, v23
	v_max_f32_e32 v16, 0, v16
	v_max_f32_e32 v17, 0, v17
	v_max_f32_e32 v18, 0, v18
	v_max_f32_e32 v20, 0, v20
	v_mul_f32_e32 v16, v16, v16
	v_mul_f32_e32 v17, v17, v17
	v_max_f32_e32 v19, 0, v19
	v_mul_f32_e32 v18, v18, v18
	v_mul_f32_e32 v20, v20, v20
	v_mul_f32_e32 v19, v19, v19
	v_cvt_pk_bf16_f32 v16, v20, v16
	v_cvt_pk_bf16_f32 v17, v17, v18
	v_cvt_pk_bf16_f32 v18, v24, v21
	v_max_f32_e32 v8, 0, v8
	v_cvt_pk_bf16_f32 v19, v22, v19
	global_store_dwordx4 v[32:33], v[16:19], off offset:256
	s_nop 1
	v_max_f32_e32 v9, 0, v9
	v_max_f32_e32 v10, 0, v10
	v_mul_f32_e32 v18, v8, v8
	v_max_f32_e32 v8, v13, v13
	v_add_u32_e32 v16, 0xb0, v134
	v_max_f32_e32 v8, 0, v8
	v_mul_f32_e32 v13, v9, v9
	v_max_f32_e32 v9, v14, v14
	v_mul_f32_e32 v14, v10, v10
	v_max_f32_e32 v10, v15, v15
	v_mad_i64_i32 v[16:17], s[2:3], v16, s4, v[130:131]
	v_max_f32_e32 v12, 0, v12
	v_mul_f32_e32 v8, v8, v8
	v_max_f32_e32 v9, 0, v9
	v_max_f32_e32 v10, 0, v10
	v_max_f32_e32 v11, 0, v11
	v_lshl_add_u64 v[16:17], v[16:17], 0, v[64:65]
	v_mul_f32_e32 v12, v12, v12
	v_mul_f32_e32 v9, v9, v9
	v_mul_f32_e32 v10, v10, v10
	v_mul_f32_e32 v11, v11, v11
	v_cvt_pk_bf16_f32 v8, v12, v8
	v_max_f32_e32 v0, 0, v0
	v_max_f32_e32 v1, 0, v1
	v_max_f32_e32 v2, 0, v2
	v_cvt_pk_bf16_f32 v9, v9, v10
	v_cvt_pk_bf16_f32 v10, v18, v13
	v_cvt_pk_bf16_f32 v11, v14, v11
	global_store_dwordx4 v[16:17], v[8:11], off
	s_nop 1
	v_mul_f32_e32 v8, v0, v0
	v_max_f32_e32 v0, v5, v5
	v_mul_f32_e32 v5, v1, v1
	v_max_f32_e32 v1, v6, v6
	v_mul_f32_e32 v6, v2, v2
	v_max_f32_e32 v2, v7, v7
	v_max_f32_e32 v0, 0, v0
	v_max_f32_e32 v1, 0, v1
	v_max_f32_e32 v2, 0, v2
	v_max_f32_e32 v3, 0, v3
	v_max_f32_e32 v4, 0, v4
	v_mul_f32_e32 v0, v0, v0
	v_mul_f32_e32 v1, v1, v1
	v_mul_f32_e32 v2, v2, v2
	v_mul_f32_e32 v3, v3, v3
	v_mul_f32_e32 v4, v4, v4
	v_cvt_pk_bf16_f32 v0, v4, v0
	v_cvt_pk_bf16_f32 v1, v1, v2
	v_cvt_pk_bf16_f32 v2, v8, v5
	v_cvt_pk_bf16_f32 v3, v6, v3
	global_store_dwordx4 v[16:17], v[0:3], off offset:256
	s_nop 1
	s_waitcnt vmcnt(0)
	s_cmpk_lt_u32 s14, 0x100
	s_movk_i32 s27, 0x1000
	s_cbranch_scc0 .LBB0_149
	s_barrier
